# GEMM loops: closing barrier of each 32-MFMA block moved up by 2 MFMAs, finishing wave runs them at s_setprio 3 then drops to 0 (barrier hand-shake overlapped with the last MFMAs)
# speedup vs baseline: 1.0195x; 1.0023x over previous
.LBB0_152:
	ds_read_b128 v[128:131], v192
	ds_read_b128 v[132:135], v192 offset:1024
	ds_read_b128 v[136:139], v192 offset:2048
	ds_read_b128 v[140:143], v192 offset:3072
	ds_read_b128 v[164:167], v193
	ds_read_b128 v[168:171], v193 offset:1024
	ds_read_b128 v[172:175], v193 offset:2048
	ds_read_b128 v[176:179], v193 offset:3072
	s_add_u32 s78, s70, 0xfffc0080
	s_addc_u32 s79, s71, -1
	s_cmp_eq_u32 s96, 12
	s_cselect_b32 s81, s11, s79
	s_cselect_b32 s80, s22, s78
	s_cselect_b32 s79, s35, s95
	s_cselect_b32 s78, s37, s94
	v_lshl_add_u64 v[228:229], s[70:71], 0, v[156:157]
	s_add_i32 m0, s82, 0xc000
	ds_read_b128 v[196:199], v194
	ds_read_b128 v[200:203], v194 offset:1024
	ds_read_b128 v[204:207], v194 offset:2048
	ds_read_b128 v[208:211], v194 offset:3072
	ds_read_b128 v[212:215], v194 offset:4096
	ds_read_b128 v[216:219], v194 offset:5120
	ds_read_b128 v[220:223], v194 offset:6144
	ds_read_b128 v[224:227], v194 offset:7168
	global_load_lds_dwordx4 v[228:229], off
	v_lshl_add_u64 v[228:229], s[70:71], 0, v[158:159]
	s_add_i32 m0, s82, 0xe000
	s_nop 0
	global_load_lds_dwordx4 v[228:229], off
	s_waitcnt vmcnt(8)
	s_waitcnt lgkmcnt(0)
	s_barrier
	s_waitcnt lgkmcnt(0)
	v_mfma_f32_16x16x32_bf16 v[124:127], v[128:131], v[196:199], v[124:127]
	v_mfma_f32_16x16x32_bf16 v[120:123], v[136:139], v[196:199], v[120:123]
	v_mfma_f32_16x16x32_bf16 v[108:111], v[128:131], v[204:207], v[108:111]
	v_mfma_f32_16x16x32_bf16 v[104:107], v[136:139], v[204:207], v[104:107]
	v_mfma_f32_16x16x32_bf16 v[92:95], v[128:131], v[212:215], v[92:95]
	v_mfma_f32_16x16x32_bf16 v[88:91], v[136:139], v[212:215], v[88:91]
	v_mfma_f32_16x16x32_bf16 v[76:79], v[128:131], v[220:223], v[76:79]
	v_mfma_f32_16x16x32_bf16 v[72:75], v[136:139], v[220:223], v[72:75]
	v_mfma_f32_16x16x32_bf16 v[124:127], v[132:135], v[200:203], v[124:127]
	v_mfma_f32_16x16x32_bf16 v[120:123], v[140:143], v[200:203], v[120:123]
	v_mfma_f32_16x16x32_bf16 v[108:111], v[132:135], v[208:211], v[108:111]
	v_mfma_f32_16x16x32_bf16 v[104:107], v[140:143], v[208:211], v[104:107]
	v_mfma_f32_16x16x32_bf16 v[92:95], v[132:135], v[216:219], v[92:95]
	v_mfma_f32_16x16x32_bf16 v[88:91], v[140:143], v[216:219], v[88:91]
	v_mfma_f32_16x16x32_bf16 v[76:79], v[132:135], v[224:227], v[76:79]
	v_mfma_f32_16x16x32_bf16 v[72:75], v[140:143], v[224:227], v[72:75]
	v_mfma_f32_16x16x32_bf16 v[116:119], v[164:167], v[196:199], v[116:119]
	v_mfma_f32_16x16x32_bf16 v[112:115], v[172:175], v[196:199], v[112:115]
	v_mfma_f32_16x16x32_bf16 v[100:103], v[164:167], v[204:207], v[100:103]
	v_mfma_f32_16x16x32_bf16 v[96:99], v[172:175], v[204:207], v[96:99]
	v_mfma_f32_16x16x32_bf16 v[84:87], v[164:167], v[212:215], v[84:87]
	v_mfma_f32_16x16x32_bf16 v[80:83], v[172:175], v[212:215], v[80:83]
	v_mfma_f32_16x16x32_bf16 v[68:71], v[164:167], v[220:223], v[68:71]
	v_mfma_f32_16x16x32_bf16 v[64:67], v[172:175], v[220:223], v[64:67]
	v_mfma_f32_16x16x32_bf16 v[116:119], v[168:171], v[200:203], v[116:119]
	v_mfma_f32_16x16x32_bf16 v[112:115], v[176:179], v[200:203], v[112:115]
	v_mfma_f32_16x16x32_bf16 v[100:103], v[168:171], v[208:211], v[100:103]
	v_mfma_f32_16x16x32_bf16 v[96:99], v[176:179], v[208:211], v[96:99]
	v_mfma_f32_16x16x32_bf16 v[84:87], v[168:171], v[216:219], v[84:87]
	v_mfma_f32_16x16x32_bf16 v[80:83], v[176:179], v[216:219], v[80:83]
	s_setprio 3
	s_barrier
	v_mfma_f32_16x16x32_bf16 v[68:71], v[168:171], v[224:227], v[68:71]
	v_mfma_f32_16x16x32_bf16 v[64:67], v[176:179], v[224:227], v[64:67]
	s_setprio 0
	s_add_i32 s97, s90, s33
	v_lshl_add_u64 v[228:229], s[78:79], 0, v[146:147]
	s_mov_b32 m0, s97
	ds_read_b128 v[196:199], v194 offset:16384
	ds_read_b128 v[200:203], v194 offset:17408
	ds_read_b128 v[204:207], v194 offset:18432
	ds_read_b128 v[208:211], v194 offset:19456
	ds_read_b128 v[212:215], v194 offset:20480
	ds_read_b128 v[216:219], v194 offset:21504
	ds_read_b128 v[220:223], v194 offset:22528
	ds_read_b128 v[224:227], v194 offset:23552
	global_load_lds_dwordx4 v[228:229], off
	s_add_i32 m0, s97, 0x2000
	s_add_u32 vcc_lo, s78, 0x40000
	v_lshl_add_u64 v[230:231], s[78:79], 0, v[150:151]
	s_addc_u32 vcc_hi, s79, 0
	s_add_i32 s97, s91, s33
	global_load_lds_dwordx4 v[230:231], off
	v_lshl_add_u64 v[232:233], vcc, 0, v[146:147]
	s_mov_b32 m0, s97
	global_load_lds_dwordx4 v[232:233], off
	v_lshl_add_u64 v[232:233], vcc, 0, v[150:151]
	s_add_i32 m0, s97, 0x2000
	s_nop 0
	global_load_lds_dwordx4 v[232:233], off
	s_waitcnt vmcnt(6)
	s_waitcnt lgkmcnt(0)
	s_barrier
	s_waitcnt lgkmcnt(0)
	v_mfma_f32_16x16x32_bf16 v[60:63], v[128:131], v[196:199], v[60:63]
	v_mfma_f32_16x16x32_bf16 v[56:59], v[136:139], v[196:199], v[56:59]
	v_mfma_f32_16x16x32_bf16 v[44:47], v[128:131], v[204:207], v[44:47]
	v_mfma_f32_16x16x32_bf16 v[40:43], v[136:139], v[204:207], v[40:43]
	v_mfma_f32_16x16x32_bf16 v[28:31], v[128:131], v[212:215], v[28:31]
	v_mfma_f32_16x16x32_bf16 v[24:27], v[136:139], v[212:215], v[24:27]
	v_mfma_f32_16x16x32_bf16 v[12:15], v[128:131], v[220:223], v[12:15]
	v_mfma_f32_16x16x32_bf16 v[8:11], v[136:139], v[220:223], v[8:11]
	v_mfma_f32_16x16x32_bf16 v[60:63], v[132:135], v[200:203], v[60:63]
	v_mfma_f32_16x16x32_bf16 v[56:59], v[140:143], v[200:203], v[56:59]
	v_mfma_f32_16x16x32_bf16 v[44:47], v[132:135], v[208:211], v[44:47]
	v_mfma_f32_16x16x32_bf16 v[40:43], v[140:143], v[208:211], v[40:43]
	v_mfma_f32_16x16x32_bf16 v[28:31], v[132:135], v[216:219], v[28:31]
	v_mfma_f32_16x16x32_bf16 v[24:27], v[140:143], v[216:219], v[24:27]
	v_mfma_f32_16x16x32_bf16 v[12:15], v[132:135], v[224:227], v[12:15]
	v_mfma_f32_16x16x32_bf16 v[8:11], v[140:143], v[224:227], v[8:11]
	v_mfma_f32_16x16x32_bf16 v[52:55], v[164:167], v[196:199], v[52:55]
	v_mfma_f32_16x16x32_bf16 v[48:51], v[172:175], v[196:199], v[48:51]
	v_mfma_f32_16x16x32_bf16 v[36:39], v[164:167], v[204:207], v[36:39]
	v_mfma_f32_16x16x32_bf16 v[32:35], v[172:175], v[204:207], v[32:35]
	v_mfma_f32_16x16x32_bf16 v[20:23], v[164:167], v[212:215], v[20:23]
	v_mfma_f32_16x16x32_bf16 v[16:19], v[172:175], v[212:215], v[16:19]
	v_mfma_f32_16x16x32_bf16 v[4:7], v[164:167], v[220:223], v[4:7]
	v_mfma_f32_16x16x32_bf16 v[0:3], v[172:175], v[220:223], v[0:3]
	v_mfma_f32_16x16x32_bf16 v[52:55], v[168:171], v[200:203], v[52:55]
	v_mfma_f32_16x16x32_bf16 v[48:51], v[176:179], v[200:203], v[48:51]
	v_mfma_f32_16x16x32_bf16 v[36:39], v[168:171], v[208:211], v[36:39]
	v_mfma_f32_16x16x32_bf16 v[32:35], v[176:179], v[208:211], v[32:35]
	v_mfma_f32_16x16x32_bf16 v[20:23], v[168:171], v[216:219], v[20:23]
	v_mfma_f32_16x16x32_bf16 v[16:19], v[176:179], v[216:219], v[16:19]
	s_setprio 3
	s_barrier
	v_mfma_f32_16x16x32_bf16 v[4:7], v[168:171], v[224:227], v[4:7]
	v_mfma_f32_16x16x32_bf16 v[0:3], v[176:179], v[224:227], v[0:3]
	s_setprio 0
	s_add_i32 s97, 0, 0x18000
	s_add_i32 vcc_lo, 0, 0x1c000
	v_add_u32_e32 v140, s97, v180
	v_add_u32_e32 v152, vcc_lo, v180
	ds_read_b128 v[128:131], v140
	ds_read_b128 v[132:135], v140 offset:1024
	ds_read_b128 v[136:139], v140 offset:2048
	ds_read_b128 v[140:143], v140 offset:3072
	ds_read_b128 v[164:167], v152
	ds_read_b128 v[168:171], v152 offset:1024
	ds_read_b128 v[172:175], v152 offset:2048
	ds_read_b128 v[176:179], v152 offset:3072
	v_lshl_add_u64 v[232:233], s[80:81], 0, v[144:145]
	s_mov_b32 m0, s82
	v_lshl_add_u64 v[234:235], s[80:81], 0, v[148:149]
	global_load_lds_dwordx4 v[232:233], off
	s_mov_b32 m0, s83
	s_nop 0
	global_load_lds_dwordx4 v[234:235], off
	s_add_u32 s80, s80, 0x40000
	s_addc_u32 s81, s81, 0
	s_mov_b32 m0, s84
	v_lshl_add_u64 v[236:237], s[80:81], 0, v[144:145]
	ds_read_b128 v[196:199], v194 offset:32768
	ds_read_b128 v[200:203], v194 offset:33792
	ds_read_b128 v[204:207], v194 offset:34816
	ds_read_b128 v[208:211], v194 offset:35840
	ds_read_b128 v[212:215], v194 offset:36864
	ds_read_b128 v[216:219], v194 offset:37888
	ds_read_b128 v[220:223], v194 offset:38912
	ds_read_b128 v[224:227], v194 offset:39936
	global_load_lds_dwordx4 v[236:237], off
	v_lshl_add_u64 v[236:237], s[80:81], 0, v[148:149]
	s_mov_b32 m0, s85
	s_nop 0
	global_load_lds_dwordx4 v[236:237], off
	s_waitcnt vmcnt(8)
	s_waitcnt lgkmcnt(0)
	s_barrier
	s_waitcnt lgkmcnt(0)
	v_mfma_f32_16x16x32_bf16 v[124:127], v[128:131], v[196:199], v[124:127]
	v_mfma_f32_16x16x32_bf16 v[120:123], v[136:139], v[196:199], v[120:123]
	v_mfma_f32_16x16x32_bf16 v[108:111], v[128:131], v[204:207], v[108:111]
	v_mfma_f32_16x16x32_bf16 v[104:107], v[136:139], v[204:207], v[104:107]
	v_mfma_f32_16x16x32_bf16 v[92:95], v[128:131], v[212:215], v[92:95]
	v_mfma_f32_16x16x32_bf16 v[88:91], v[136:139], v[212:215], v[88:91]
	v_mfma_f32_16x16x32_bf16 v[76:79], v[128:131], v[220:223], v[76:79]
	v_mfma_f32_16x16x32_bf16 v[72:75], v[136:139], v[220:223], v[72:75]
	v_mfma_f32_16x16x32_bf16 v[124:127], v[132:135], v[200:203], v[124:127]
	v_mfma_f32_16x16x32_bf16 v[120:123], v[140:143], v[200:203], v[120:123]
	v_mfma_f32_16x16x32_bf16 v[108:111], v[132:135], v[208:211], v[108:111]
	v_mfma_f32_16x16x32_bf16 v[104:107], v[140:143], v[208:211], v[104:107]
	v_mfma_f32_16x16x32_bf16 v[92:95], v[132:135], v[216:219], v[92:95]
	v_mfma_f32_16x16x32_bf16 v[88:91], v[140:143], v[216:219], v[88:91]
	v_mfma_f32_16x16x32_bf16 v[76:79], v[132:135], v[224:227], v[76:79]
	v_mfma_f32_16x16x32_bf16 v[72:75], v[140:143], v[224:227], v[72:75]
	v_mfma_f32_16x16x32_bf16 v[116:119], v[164:167], v[196:199], v[116:119]
	v_mfma_f32_16x16x32_bf16 v[112:115], v[172:175], v[196:199], v[112:115]
	v_mfma_f32_16x16x32_bf16 v[100:103], v[164:167], v[204:207], v[100:103]
	v_mfma_f32_16x16x32_bf16 v[96:99], v[172:175], v[204:207], v[96:99]
	v_mfma_f32_16x16x32_bf16 v[84:87], v[164:167], v[212:215], v[84:87]
	v_mfma_f32_16x16x32_bf16 v[80:83], v[172:175], v[212:215], v[80:83]
	v_mfma_f32_16x16x32_bf16 v[68:71], v[164:167], v[220:223], v[68:71]
	v_mfma_f32_16x16x32_bf16 v[64:67], v[172:175], v[220:223], v[64:67]
	v_mfma_f32_16x16x32_bf16 v[116:119], v[168:171], v[200:203], v[116:119]
	v_mfma_f32_16x16x32_bf16 v[112:115], v[176:179], v[200:203], v[112:115]
	v_mfma_f32_16x16x32_bf16 v[100:103], v[168:171], v[208:211], v[100:103]
	v_mfma_f32_16x16x32_bf16 v[96:99], v[176:179], v[208:211], v[96:99]
	v_mfma_f32_16x16x32_bf16 v[84:87], v[168:171], v[216:219], v[84:87]
	v_mfma_f32_16x16x32_bf16 v[80:83], v[176:179], v[216:219], v[80:83]
	s_setprio 3
	s_barrier
	v_mfma_f32_16x16x32_bf16 v[68:71], v[168:171], v[224:227], v[68:71]
	v_mfma_f32_16x16x32_bf16 v[64:67], v[176:179], v[224:227], v[64:67]
	s_setprio 0
	s_add_i32 s80, s97, s33
	v_lshl_add_u64 v[228:229], v[228:229], 0, s[26:27]
	s_mov_b32 m0, s80
	ds_read_b128 v[196:199], v194 offset:49152
	ds_read_b128 v[200:203], v194 offset:50176
	ds_read_b128 v[204:207], v194 offset:51200
	ds_read_b128 v[208:211], v194 offset:52224
	ds_read_b128 v[212:215], v194 offset:53248
	ds_read_b128 v[216:219], v194 offset:54272
	ds_read_b128 v[220:223], v194 offset:55296
	ds_read_b128 v[224:227], v194 offset:56320
	global_load_lds_dwordx4 v[228:229], off
	s_add_i32 m0, s80, 0x2000
	s_add_u32 s78, s78, 0x40080
	v_lshl_add_u64 v[228:229], v[230:231], 0, s[26:27]
	s_addc_u32 s79, s79, 0
	s_add_i32 s80, vcc_lo, s33
	global_load_lds_dwordx4 v[228:229], off
	v_lshl_add_u64 v[228:229], s[78:79], 0, v[146:147]
	s_mov_b32 m0, s80
	s_nop 0
	global_load_lds_dwordx4 v[228:229], off
	v_lshl_add_u64 v[228:229], s[78:79], 0, v[150:151]
	s_add_i32 m0, s80, 0x2000
	s_nop 0
	global_load_lds_dwordx4 v[228:229], off
	s_waitcnt vmcnt(6)
	s_waitcnt lgkmcnt(0)
	s_barrier
	s_waitcnt lgkmcnt(0)
	v_mfma_f32_16x16x32_bf16 v[60:63], v[128:131], v[196:199], v[60:63]
	v_mfma_f32_16x16x32_bf16 v[56:59], v[136:139], v[196:199], v[56:59]
	v_mfma_f32_16x16x32_bf16 v[44:47], v[128:131], v[204:207], v[44:47]
	v_mfma_f32_16x16x32_bf16 v[40:43], v[136:139], v[204:207], v[40:43]
	v_mfma_f32_16x16x32_bf16 v[28:31], v[128:131], v[212:215], v[28:31]
	v_mfma_f32_16x16x32_bf16 v[24:27], v[136:139], v[212:215], v[24:27]
	v_mfma_f32_16x16x32_bf16 v[12:15], v[128:131], v[220:223], v[12:15]
	v_mfma_f32_16x16x32_bf16 v[8:11], v[136:139], v[220:223], v[8:11]
	v_mfma_f32_16x16x32_bf16 v[60:63], v[132:135], v[200:203], v[60:63]
	v_mfma_f32_16x16x32_bf16 v[56:59], v[140:143], v[200:203], v[56:59]
	v_mfma_f32_16x16x32_bf16 v[44:47], v[132:135], v[208:211], v[44:47]
	v_mfma_f32_16x16x32_bf16 v[40:43], v[140:143], v[208:211], v[40:43]
	v_mfma_f32_16x16x32_bf16 v[28:31], v[132:135], v[216:219], v[28:31]
	v_mfma_f32_16x16x32_bf16 v[24:27], v[140:143], v[216:219], v[24:27]
	v_mfma_f32_16x16x32_bf16 v[12:15], v[132:135], v[224:227], v[12:15]
	v_mfma_f32_16x16x32_bf16 v[8:11], v[140:143], v[224:227], v[8:11]
	v_mfma_f32_16x16x32_bf16 v[52:55], v[164:167], v[196:199], v[52:55]
	v_mfma_f32_16x16x32_bf16 v[48:51], v[172:175], v[196:199], v[48:51]
	v_mfma_f32_16x16x32_bf16 v[36:39], v[164:167], v[204:207], v[36:39]
	v_mfma_f32_16x16x32_bf16 v[32:35], v[172:175], v[204:207], v[32:35]
	v_mfma_f32_16x16x32_bf16 v[20:23], v[164:167], v[212:215], v[20:23]
	v_mfma_f32_16x16x32_bf16 v[16:19], v[172:175], v[212:215], v[16:19]
	v_mfma_f32_16x16x32_bf16 v[4:7], v[164:167], v[220:223], v[4:7]
	v_mfma_f32_16x16x32_bf16 v[0:3], v[172:175], v[220:223], v[0:3]
	v_mfma_f32_16x16x32_bf16 v[52:55], v[168:171], v[200:203], v[52:55]
	v_mfma_f32_16x16x32_bf16 v[48:51], v[176:179], v[200:203], v[48:51]
	v_mfma_f32_16x16x32_bf16 v[36:39], v[168:171], v[208:211], v[36:39]
	v_mfma_f32_16x16x32_bf16 v[32:35], v[176:179], v[208:211], v[32:35]
	v_mfma_f32_16x16x32_bf16 v[20:23], v[168:171], v[216:219], v[20:23]
	v_mfma_f32_16x16x32_bf16 v[16:19], v[176:179], v[216:219], v[16:19]
	s_setprio 3
	s_barrier
	v_mfma_f32_16x16x32_bf16 v[4:7], v[168:171], v[224:227], v[4:7]
	v_mfma_f32_16x16x32_bf16 v[0:3], v[176:179], v[224:227], v[0:3]
	s_setprio 0
	v_lshl_add_u64 v[228:229], v[232:233], 0, s[26:27]
	s_mov_b32 m0, s87
	s_nop 0
	global_load_lds_dwordx4 v[228:229], off
	v_lshl_add_u64 v[228:229], v[234:235], 0, s[26:27]
	s_mov_b32 m0, s88
	s_nop 0
	global_load_lds_dwordx4 v[228:229], off
	s_add_i32 s96, s96, 2
	s_add_u32 s70, s70, 0x100
	s_addc_u32 s71, s71, 0
	s_add_u32 s94, s94, 0x100
	s_addc_u32 s95, s95, 0
	s_cmp_gt_u32 s96, 13
	s_cbranch_scc0 .LBB0_152
	s_and_b64 vcc, exec, s[28:29]
	s_cbranch_vccz .LBB0_155
	s_barrier

.LBB0_617:
	ds_read_b128 v[144:147], v151
	ds_read_b128 v[156:159], v151 offset:1024
	ds_read_b128 v[160:163], v151 offset:2048
	ds_read_b128 v[164:167], v151 offset:3072
	ds_read_b128 v[168:171], v152
	ds_read_b128 v[172:175], v152 offset:1024
	ds_read_b128 v[176:179], v152 offset:2048
	ds_read_b128 v[184:187], v152 offset:3072
	s_add_u32 s26, s24, 0xfffc0080
	s_addc_u32 s27, s25, -1
	s_cmp_eq_u32 s51, 12
	s_cselect_b32 s29, s17, s27
	s_cselect_b32 s28, s23, s26
	s_cselect_b32 s27, s15, s50
	s_cselect_b32 s26, s46, s47
	v_lshl_add_u64 v[220:221], s[24:25], 0, v[136:137]
	s_add_i32 m0, s34, 0xc000
	ds_read_b128 v[188:191], v153
	ds_read_b128 v[192:195], v153 offset:1024
	ds_read_b128 v[196:199], v153 offset:2048
	ds_read_b128 v[200:203], v153 offset:3072
	ds_read_b128 v[204:207], v153 offset:4096
	ds_read_b128 v[208:211], v153 offset:5120
	ds_read_b128 v[212:215], v153 offset:6144
	ds_read_b128 v[216:219], v153 offset:7168
	global_load_lds_dwordx4 v[220:221], off
	v_lshl_add_u64 v[220:221], s[24:25], 0, v[138:139]
	s_add_i32 m0, s34, 0xe000
	s_nop 0
	global_load_lds_dwordx4 v[220:221], off
	s_waitcnt vmcnt(8)
	s_waitcnt lgkmcnt(0)
	s_barrier
	s_waitcnt lgkmcnt(0)
	v_mfma_f32_16x16x32_bf16 v[124:127], v[144:147], v[188:191], v[124:127]
	v_mfma_f32_16x16x32_bf16 v[120:123], v[160:163], v[188:191], v[120:123]
	v_mfma_f32_16x16x32_bf16 v[108:111], v[144:147], v[196:199], v[108:111]
	v_mfma_f32_16x16x32_bf16 v[104:107], v[160:163], v[196:199], v[104:107]
	v_mfma_f32_16x16x32_bf16 v[92:95], v[144:147], v[204:207], v[92:95]
	v_mfma_f32_16x16x32_bf16 v[88:91], v[160:163], v[204:207], v[88:91]
	v_mfma_f32_16x16x32_bf16 v[76:79], v[144:147], v[212:215], v[76:79]
	v_mfma_f32_16x16x32_bf16 v[72:75], v[160:163], v[212:215], v[72:75]
	v_mfma_f32_16x16x32_bf16 v[124:127], v[156:159], v[192:195], v[124:127]
	v_mfma_f32_16x16x32_bf16 v[120:123], v[164:167], v[192:195], v[120:123]
	v_mfma_f32_16x16x32_bf16 v[108:111], v[156:159], v[200:203], v[108:111]
	v_mfma_f32_16x16x32_bf16 v[104:107], v[164:167], v[200:203], v[104:107]
	v_mfma_f32_16x16x32_bf16 v[92:95], v[156:159], v[208:211], v[92:95]
	v_mfma_f32_16x16x32_bf16 v[88:91], v[164:167], v[208:211], v[88:91]
	v_mfma_f32_16x16x32_bf16 v[76:79], v[156:159], v[216:219], v[76:79]
	v_mfma_f32_16x16x32_bf16 v[72:75], v[164:167], v[216:219], v[72:75]
	v_mfma_f32_16x16x32_bf16 v[116:119], v[168:171], v[188:191], v[116:119]
	v_mfma_f32_16x16x32_bf16 v[112:115], v[176:179], v[188:191], v[112:115]
	v_mfma_f32_16x16x32_bf16 v[100:103], v[168:171], v[196:199], v[100:103]
	v_mfma_f32_16x16x32_bf16 v[96:99], v[176:179], v[196:199], v[96:99]
	v_mfma_f32_16x16x32_bf16 v[84:87], v[168:171], v[204:207], v[84:87]
	v_mfma_f32_16x16x32_bf16 v[80:83], v[176:179], v[204:207], v[80:83]
	v_mfma_f32_16x16x32_bf16 v[68:71], v[168:171], v[212:215], v[68:71]
	v_mfma_f32_16x16x32_bf16 v[64:67], v[176:179], v[212:215], v[64:67]
	v_mfma_f32_16x16x32_bf16 v[116:119], v[172:175], v[192:195], v[116:119]
	v_mfma_f32_16x16x32_bf16 v[112:115], v[184:187], v[192:195], v[112:115]
	v_mfma_f32_16x16x32_bf16 v[100:103], v[172:175], v[200:203], v[100:103]
	v_mfma_f32_16x16x32_bf16 v[96:99], v[184:187], v[200:203], v[96:99]
	v_mfma_f32_16x16x32_bf16 v[84:87], v[172:175], v[208:211], v[84:87]
	v_mfma_f32_16x16x32_bf16 v[80:83], v[184:187], v[208:211], v[80:83]
	s_setprio 3
	s_barrier
	v_mfma_f32_16x16x32_bf16 v[68:71], v[172:175], v[216:219], v[68:71]
	v_mfma_f32_16x16x32_bf16 v[64:67], v[184:187], v[216:219], v[64:67]
	s_setprio 0
	s_add_i32 s52, s41, s33
	v_lshl_add_u64 v[220:221], s[26:27], 0, v[130:131]
	s_mov_b32 m0, s52
	ds_read_b128 v[188:191], v153 offset:16384
	ds_read_b128 v[192:195], v153 offset:17408
	ds_read_b128 v[196:199], v153 offset:18432
	ds_read_b128 v[200:203], v153 offset:19456
	ds_read_b128 v[204:207], v153 offset:20480
	ds_read_b128 v[208:211], v153 offset:21504
	ds_read_b128 v[212:215], v153 offset:22528
	ds_read_b128 v[216:219], v153 offset:23552
	global_load_lds_dwordx4 v[220:221], off
	s_add_i32 m0, s52, 0x2000
	s_add_u32 s52, s26, 0x40000
	v_lshl_add_u64 v[222:223], s[26:27], 0, v[134:135]
	s_addc_u32 s53, s27, 0
	s_add_i32 s54, s42, s33
	global_load_lds_dwordx4 v[222:223], off
	v_lshl_add_u64 v[224:225], s[52:53], 0, v[130:131]
	s_mov_b32 m0, s54
	global_load_lds_dwordx4 v[224:225], off
	v_lshl_add_u64 v[224:225], s[52:53], 0, v[134:135]
	s_add_i32 m0, s54, 0x2000
	s_nop 0
	global_load_lds_dwordx4 v[224:225], off
	s_waitcnt vmcnt(6)
	s_waitcnt lgkmcnt(0)
	s_barrier
	s_waitcnt lgkmcnt(0)
	v_mfma_f32_16x16x32_bf16 v[60:63], v[144:147], v[188:191], v[60:63]
	v_mfma_f32_16x16x32_bf16 v[56:59], v[160:163], v[188:191], v[56:59]
	v_mfma_f32_16x16x32_bf16 v[44:47], v[144:147], v[196:199], v[44:47]
	v_mfma_f32_16x16x32_bf16 v[40:43], v[160:163], v[196:199], v[40:43]
	v_mfma_f32_16x16x32_bf16 v[28:31], v[144:147], v[204:207], v[28:31]
	v_mfma_f32_16x16x32_bf16 v[24:27], v[160:163], v[204:207], v[24:27]
	v_mfma_f32_16x16x32_bf16 v[12:15], v[144:147], v[212:215], v[12:15]
	v_mfma_f32_16x16x32_bf16 v[8:11], v[160:163], v[212:215], v[8:11]
	v_mfma_f32_16x16x32_bf16 v[60:63], v[156:159], v[192:195], v[60:63]
	v_mfma_f32_16x16x32_bf16 v[56:59], v[164:167], v[192:195], v[56:59]
	v_mfma_f32_16x16x32_bf16 v[44:47], v[156:159], v[200:203], v[44:47]
	v_mfma_f32_16x16x32_bf16 v[40:43], v[164:167], v[200:203], v[40:43]
	v_mfma_f32_16x16x32_bf16 v[28:31], v[156:159], v[208:211], v[28:31]
	v_mfma_f32_16x16x32_bf16 v[24:27], v[164:167], v[208:211], v[24:27]
	v_mfma_f32_16x16x32_bf16 v[12:15], v[156:159], v[216:219], v[12:15]
	v_mfma_f32_16x16x32_bf16 v[8:11], v[164:167], v[216:219], v[8:11]
	v_mfma_f32_16x16x32_bf16 v[52:55], v[168:171], v[188:191], v[52:55]
	v_mfma_f32_16x16x32_bf16 v[48:51], v[176:179], v[188:191], v[48:51]
	v_mfma_f32_16x16x32_bf16 v[36:39], v[168:171], v[196:199], v[36:39]
	v_mfma_f32_16x16x32_bf16 v[32:35], v[176:179], v[196:199], v[32:35]
	v_mfma_f32_16x16x32_bf16 v[20:23], v[168:171], v[204:207], v[20:23]
	v_mfma_f32_16x16x32_bf16 v[16:19], v[176:179], v[204:207], v[16:19]
	v_mfma_f32_16x16x32_bf16 v[4:7], v[168:171], v[212:215], v[4:7]
	v_mfma_f32_16x16x32_bf16 v[0:3], v[176:179], v[212:215], v[0:3]
	v_mfma_f32_16x16x32_bf16 v[52:55], v[172:175], v[192:195], v[52:55]
	v_mfma_f32_16x16x32_bf16 v[48:51], v[184:187], v[192:195], v[48:51]
	v_mfma_f32_16x16x32_bf16 v[36:39], v[172:175], v[200:203], v[36:39]
	v_mfma_f32_16x16x32_bf16 v[32:35], v[184:187], v[200:203], v[32:35]
	v_mfma_f32_16x16x32_bf16 v[20:23], v[172:175], v[208:211], v[20:23]
	v_mfma_f32_16x16x32_bf16 v[16:19], v[184:187], v[208:211], v[16:19]
	s_setprio 3
	s_barrier
	v_mfma_f32_16x16x32_bf16 v[4:7], v[172:175], v[216:219], v[4:7]
	v_mfma_f32_16x16x32_bf16 v[0:3], v[184:187], v[216:219], v[0:3]
	s_setprio 0
	s_add_i32 s52, 0, 0x18000
	v_add_u32_e32 v155, s52, v149
	s_add_i32 s53, 0, 0x1c000
	ds_read_b128 v[144:147], v155
	ds_read_b128 v[156:159], v155 offset:1024
	ds_read_b128 v[160:163], v155 offset:2048
	ds_read_b128 v[164:167], v155 offset:3072
	v_add_u32_e32 v155, s53, v149
	ds_read_b128 v[168:171], v155
	ds_read_b128 v[172:175], v155 offset:1024
	ds_read_b128 v[176:179], v155 offset:2048
	ds_read_b128 v[184:187], v155 offset:3072
	v_lshl_add_u64 v[224:225], s[28:29], 0, v[128:129]
	s_mov_b32 m0, s34
	v_lshl_add_u64 v[226:227], s[28:29], 0, v[132:133]
	global_load_lds_dwordx4 v[224:225], off
	s_mov_b32 m0, s35
	s_nop 0
	global_load_lds_dwordx4 v[226:227], off
	s_add_u32 s28, s28, 0x40000
	s_addc_u32 s29, s29, 0
	s_mov_b32 m0, s36
	v_lshl_add_u64 v[228:229], s[28:29], 0, v[128:129]
	ds_read_b128 v[188:191], v153 offset:32768
	ds_read_b128 v[192:195], v153 offset:33792
	ds_read_b128 v[196:199], v153 offset:34816
	ds_read_b128 v[200:203], v153 offset:35840
	ds_read_b128 v[204:207], v153 offset:36864
	ds_read_b128 v[208:211], v153 offset:37888
	ds_read_b128 v[212:215], v153 offset:38912
	ds_read_b128 v[216:219], v153 offset:39936
	global_load_lds_dwordx4 v[228:229], off
	v_lshl_add_u64 v[228:229], s[28:29], 0, v[132:133]
	s_mov_b32 m0, s37
	s_nop 0
	global_load_lds_dwordx4 v[228:229], off
	s_waitcnt vmcnt(8)
	s_waitcnt lgkmcnt(0)
	s_barrier
	s_waitcnt lgkmcnt(0)
	v_mfma_f32_16x16x32_bf16 v[124:127], v[144:147], v[188:191], v[124:127]
	v_mfma_f32_16x16x32_bf16 v[120:123], v[160:163], v[188:191], v[120:123]
	v_mfma_f32_16x16x32_bf16 v[108:111], v[144:147], v[196:199], v[108:111]
	v_mfma_f32_16x16x32_bf16 v[104:107], v[160:163], v[196:199], v[104:107]
	v_mfma_f32_16x16x32_bf16 v[92:95], v[144:147], v[204:207], v[92:95]
	v_mfma_f32_16x16x32_bf16 v[88:91], v[160:163], v[204:207], v[88:91]
	v_mfma_f32_16x16x32_bf16 v[76:79], v[144:147], v[212:215], v[76:79]
	v_mfma_f32_16x16x32_bf16 v[72:75], v[160:163], v[212:215], v[72:75]
	v_mfma_f32_16x16x32_bf16 v[124:127], v[156:159], v[192:195], v[124:127]
	v_mfma_f32_16x16x32_bf16 v[120:123], v[164:167], v[192:195], v[120:123]
	v_mfma_f32_16x16x32_bf16 v[108:111], v[156:159], v[200:203], v[108:111]
	v_mfma_f32_16x16x32_bf16 v[104:107], v[164:167], v[200:203], v[104:107]
	v_mfma_f32_16x16x32_bf16 v[92:95], v[156:159], v[208:211], v[92:95]
	v_mfma_f32_16x16x32_bf16 v[88:91], v[164:167], v[208:211], v[88:91]
	v_mfma_f32_16x16x32_bf16 v[76:79], v[156:159], v[216:219], v[76:79]
	v_mfma_f32_16x16x32_bf16 v[72:75], v[164:167], v[216:219], v[72:75]
	v_mfma_f32_16x16x32_bf16 v[116:119], v[168:171], v[188:191], v[116:119]
	v_mfma_f32_16x16x32_bf16 v[112:115], v[176:179], v[188:191], v[112:115]
	v_mfma_f32_16x16x32_bf16 v[100:103], v[168:171], v[196:199], v[100:103]
	v_mfma_f32_16x16x32_bf16 v[96:99], v[176:179], v[196:199], v[96:99]
	v_mfma_f32_16x16x32_bf16 v[84:87], v[168:171], v[204:207], v[84:87]
	v_mfma_f32_16x16x32_bf16 v[80:83], v[176:179], v[204:207], v[80:83]
	v_mfma_f32_16x16x32_bf16 v[68:71], v[168:171], v[212:215], v[68:71]
	v_mfma_f32_16x16x32_bf16 v[64:67], v[176:179], v[212:215], v[64:67]
	v_mfma_f32_16x16x32_bf16 v[116:119], v[172:175], v[192:195], v[116:119]
	v_mfma_f32_16x16x32_bf16 v[112:115], v[184:187], v[192:195], v[112:115]
	v_mfma_f32_16x16x32_bf16 v[100:103], v[172:175], v[200:203], v[100:103]
	v_mfma_f32_16x16x32_bf16 v[96:99], v[184:187], v[200:203], v[96:99]
	v_mfma_f32_16x16x32_bf16 v[84:87], v[172:175], v[208:211], v[84:87]
	v_mfma_f32_16x16x32_bf16 v[80:83], v[184:187], v[208:211], v[80:83]
	s_setprio 3
	s_barrier
	v_mfma_f32_16x16x32_bf16 v[68:71], v[172:175], v[216:219], v[68:71]
	v_mfma_f32_16x16x32_bf16 v[64:67], v[184:187], v[216:219], v[64:67]
	s_setprio 0
	s_add_i32 s28, s52, s33
	v_lshl_add_u64 v[220:221], v[220:221], 0, s[10:11]
	s_mov_b32 m0, s28
	ds_read_b128 v[188:191], v153 offset:49152
	ds_read_b128 v[192:195], v153 offset:50176
	ds_read_b128 v[196:199], v153 offset:51200
	ds_read_b128 v[200:203], v153 offset:52224
	ds_read_b128 v[204:207], v153 offset:53248
	ds_read_b128 v[208:211], v153 offset:54272
	ds_read_b128 v[212:215], v153 offset:55296
	ds_read_b128 v[216:219], v153 offset:56320
	global_load_lds_dwordx4 v[220:221], off
	s_add_i32 m0, s28, 0x2000
	s_add_u32 s26, s26, 0x40080
	v_lshl_add_u64 v[220:221], v[222:223], 0, s[10:11]
	s_addc_u32 s27, s27, 0
	s_add_i32 s28, s53, s33
	global_load_lds_dwordx4 v[220:221], off
	v_lshl_add_u64 v[220:221], s[26:27], 0, v[130:131]
	s_mov_b32 m0, s28
	s_nop 0
	global_load_lds_dwordx4 v[220:221], off
	v_lshl_add_u64 v[220:221], s[26:27], 0, v[134:135]
	s_add_i32 m0, s28, 0x2000
	s_nop 0
	global_load_lds_dwordx4 v[220:221], off
	s_waitcnt vmcnt(6)
	s_waitcnt lgkmcnt(0)
	s_barrier
	s_waitcnt lgkmcnt(0)
	v_mfma_f32_16x16x32_bf16 v[60:63], v[144:147], v[188:191], v[60:63]
	v_mfma_f32_16x16x32_bf16 v[56:59], v[160:163], v[188:191], v[56:59]
	v_mfma_f32_16x16x32_bf16 v[44:47], v[144:147], v[196:199], v[44:47]
	v_mfma_f32_16x16x32_bf16 v[40:43], v[160:163], v[196:199], v[40:43]
	v_mfma_f32_16x16x32_bf16 v[28:31], v[144:147], v[204:207], v[28:31]
	v_mfma_f32_16x16x32_bf16 v[24:27], v[160:163], v[204:207], v[24:27]
	v_mfma_f32_16x16x32_bf16 v[12:15], v[144:147], v[212:215], v[12:15]
	v_mfma_f32_16x16x32_bf16 v[8:11], v[160:163], v[212:215], v[8:11]
	v_mfma_f32_16x16x32_bf16 v[60:63], v[156:159], v[192:195], v[60:63]
	v_mfma_f32_16x16x32_bf16 v[56:59], v[164:167], v[192:195], v[56:59]
	v_mfma_f32_16x16x32_bf16 v[44:47], v[156:159], v[200:203], v[44:47]
	v_mfma_f32_16x16x32_bf16 v[40:43], v[164:167], v[200:203], v[40:43]
	v_mfma_f32_16x16x32_bf16 v[28:31], v[156:159], v[208:211], v[28:31]
	v_mfma_f32_16x16x32_bf16 v[24:27], v[164:167], v[208:211], v[24:27]
	v_mfma_f32_16x16x32_bf16 v[12:15], v[156:159], v[216:219], v[12:15]
	v_mfma_f32_16x16x32_bf16 v[8:11], v[164:167], v[216:219], v[8:11]
	v_mfma_f32_16x16x32_bf16 v[52:55], v[168:171], v[188:191], v[52:55]
	v_mfma_f32_16x16x32_bf16 v[48:51], v[176:179], v[188:191], v[48:51]
	v_mfma_f32_16x16x32_bf16 v[36:39], v[168:171], v[196:199], v[36:39]
	v_mfma_f32_16x16x32_bf16 v[32:35], v[176:179], v[196:199], v[32:35]
	v_mfma_f32_16x16x32_bf16 v[20:23], v[168:171], v[204:207], v[20:23]
	v_mfma_f32_16x16x32_bf16 v[16:19], v[176:179], v[204:207], v[16:19]
	v_mfma_f32_16x16x32_bf16 v[4:7], v[168:171], v[212:215], v[4:7]
	v_mfma_f32_16x16x32_bf16 v[0:3], v[176:179], v[212:215], v[0:3]
	v_mfma_f32_16x16x32_bf16 v[52:55], v[172:175], v[192:195], v[52:55]
	v_mfma_f32_16x16x32_bf16 v[48:51], v[184:187], v[192:195], v[48:51]
	v_mfma_f32_16x16x32_bf16 v[36:39], v[172:175], v[200:203], v[36:39]
	v_mfma_f32_16x16x32_bf16 v[32:35], v[184:187], v[200:203], v[32:35]
	v_mfma_f32_16x16x32_bf16 v[20:23], v[172:175], v[208:211], v[20:23]
	v_mfma_f32_16x16x32_bf16 v[16:19], v[184:187], v[208:211], v[16:19]
	s_setprio 3
	s_barrier
	v_mfma_f32_16x16x32_bf16 v[4:7], v[172:175], v[216:219], v[4:7]
	v_mfma_f32_16x16x32_bf16 v[0:3], v[184:187], v[216:219], v[0:3]
	s_setprio 0
	v_lshl_add_u64 v[220:221], v[224:225], 0, s[10:11]
	s_mov_b32 m0, s39
	s_nop 0
	global_load_lds_dwordx4 v[220:221], off
	v_lshl_add_u64 v[220:221], v[226:227], 0, s[10:11]
	s_mov_b32 m0, s40
	s_nop 0
	global_load_lds_dwordx4 v[220:221], off
	s_add_i32 s51, s51, 2
	s_add_u32 s24, s24, 0x100
	s_addc_u32 s25, s25, 0
	s_add_u32 s47, s47, 0x100
	s_addc_u32 s50, s50, 0
	s_cmp_gt_u32 s51, 13
	s_cbranch_scc0 .LBB0_617
	s_and_b64 vcc, exec, s[12:13]
	s_cbranch_vccz .LBB0_620
	s_barrier

.LBB0_705:
	ds_read_b128 v[154:157], v151
	ds_read_b128 v[158:161], v151 offset:1024
	ds_read_b128 v[162:165], v151 offset:2048
	ds_read_b128 v[166:169], v151 offset:3072
	ds_read_b128 v[170:173], v152
	ds_read_b128 v[174:177], v152 offset:1024
	ds_read_b128 v[184:187], v152 offset:2048
	ds_read_b128 v[188:191], v152 offset:3072
	s_add_u32 s22, s20, 0xfffc0080
	s_addc_u32 s23, s21, -1
	s_cmp_eq_u32 s50, 12
	s_cselect_b32 s25, s13, s23
	s_cselect_b32 s24, s42, s22
	s_cselect_b32 s23, s11, s47
	s_cselect_b32 s22, s43, s46
	v_lshl_add_u64 v[178:179], s[20:21], 0, v[136:137]
	s_add_i32 m0, s19, 0xc000
	ds_read_b128 v[192:195], v153
	ds_read_b128 v[196:199], v153 offset:1024
	ds_read_b128 v[200:203], v153 offset:2048
	ds_read_b128 v[204:207], v153 offset:3072
	ds_read_b128 v[208:211], v153 offset:4096
	ds_read_b128 v[212:215], v153 offset:5120
	ds_read_b128 v[216:219], v153 offset:6144
	ds_read_b128 v[220:223], v153 offset:7168
	global_load_lds_dwordx4 v[178:179], off
	v_lshl_add_u64 v[178:179], s[20:21], 0, v[138:139]
	s_add_i32 m0, s19, 0xe000
	s_nop 0
	global_load_lds_dwordx4 v[178:179], off
	s_waitcnt vmcnt(8)
	s_waitcnt lgkmcnt(0)
	s_barrier
	s_waitcnt lgkmcnt(0)
	v_mfma_f32_16x16x32_bf16 v[124:127], v[154:157], v[192:195], v[124:127]
	v_mfma_f32_16x16x32_bf16 v[116:119], v[162:165], v[192:195], v[116:119]
	v_mfma_f32_16x16x32_bf16 v[108:111], v[154:157], v[200:203], v[108:111]
	v_mfma_f32_16x16x32_bf16 v[100:103], v[162:165], v[200:203], v[100:103]
	v_mfma_f32_16x16x32_bf16 v[92:95], v[154:157], v[208:211], v[92:95]
	v_mfma_f32_16x16x32_bf16 v[84:87], v[162:165], v[208:211], v[84:87]
	v_mfma_f32_16x16x32_bf16 v[76:79], v[154:157], v[216:219], v[76:79]
	v_mfma_f32_16x16x32_bf16 v[68:71], v[162:165], v[216:219], v[68:71]
	v_mfma_f32_16x16x32_bf16 v[124:127], v[158:161], v[196:199], v[124:127]
	v_mfma_f32_16x16x32_bf16 v[116:119], v[166:169], v[196:199], v[116:119]
	v_mfma_f32_16x16x32_bf16 v[108:111], v[158:161], v[204:207], v[108:111]
	v_mfma_f32_16x16x32_bf16 v[100:103], v[166:169], v[204:207], v[100:103]
	v_mfma_f32_16x16x32_bf16 v[92:95], v[158:161], v[212:215], v[92:95]
	v_mfma_f32_16x16x32_bf16 v[84:87], v[166:169], v[212:215], v[84:87]
	v_mfma_f32_16x16x32_bf16 v[76:79], v[158:161], v[220:223], v[76:79]
	v_mfma_f32_16x16x32_bf16 v[68:71], v[166:169], v[220:223], v[68:71]
	v_mfma_f32_16x16x32_bf16 v[120:123], v[170:173], v[192:195], v[120:123]
	v_mfma_f32_16x16x32_bf16 v[112:115], v[184:187], v[192:195], v[112:115]
	v_mfma_f32_16x16x32_bf16 v[104:107], v[170:173], v[200:203], v[104:107]
	v_mfma_f32_16x16x32_bf16 v[96:99], v[184:187], v[200:203], v[96:99]
	v_mfma_f32_16x16x32_bf16 v[88:91], v[170:173], v[208:211], v[88:91]
	v_mfma_f32_16x16x32_bf16 v[80:83], v[184:187], v[208:211], v[80:83]
	v_mfma_f32_16x16x32_bf16 v[72:75], v[170:173], v[216:219], v[72:75]
	v_mfma_f32_16x16x32_bf16 v[64:67], v[184:187], v[216:219], v[64:67]
	v_mfma_f32_16x16x32_bf16 v[120:123], v[174:177], v[196:199], v[120:123]
	v_mfma_f32_16x16x32_bf16 v[112:115], v[188:191], v[196:199], v[112:115]
	v_mfma_f32_16x16x32_bf16 v[104:107], v[174:177], v[204:207], v[104:107]
	v_mfma_f32_16x16x32_bf16 v[96:99], v[188:191], v[204:207], v[96:99]
	v_mfma_f32_16x16x32_bf16 v[88:91], v[174:177], v[212:215], v[88:91]
	v_mfma_f32_16x16x32_bf16 v[80:83], v[188:191], v[212:215], v[80:83]
	s_setprio 3
	s_barrier
	v_mfma_f32_16x16x32_bf16 v[72:75], v[174:177], v[220:223], v[72:75]
	v_mfma_f32_16x16x32_bf16 v[64:67], v[188:191], v[220:223], v[64:67]
	s_setprio 0
	s_add_i32 s51, s36, s28
	v_lshl_add_u64 v[178:179], s[22:23], 0, v[132:133]
	s_mov_b32 m0, s51
	ds_read_b128 v[192:195], v153 offset:16384
	ds_read_b128 v[196:199], v153 offset:17408
	ds_read_b128 v[200:203], v153 offset:18432
	ds_read_b128 v[204:207], v153 offset:19456
	ds_read_b128 v[208:211], v153 offset:20480
	ds_read_b128 v[212:215], v153 offset:21504
	ds_read_b128 v[216:219], v153 offset:22528
	ds_read_b128 v[220:223], v153 offset:23552
	global_load_lds_dwordx4 v[178:179], off
	s_add_i32 m0, s51, 0x2000
	s_add_u32 s52, s22, 0x40000
	v_lshl_add_u64 v[224:225], s[22:23], 0, v[128:129]
	s_addc_u32 s53, s23, 0
	s_add_i32 s51, s37, s28
	global_load_lds_dwordx4 v[224:225], off
	v_lshl_add_u64 v[226:227], s[52:53], 0, v[132:133]
	s_mov_b32 m0, s51
	global_load_lds_dwordx4 v[226:227], off
	v_lshl_add_u64 v[226:227], s[52:53], 0, v[128:129]
	s_add_i32 m0, s51, 0x2000
	s_nop 0
	global_load_lds_dwordx4 v[226:227], off
	s_waitcnt vmcnt(6)
	s_waitcnt lgkmcnt(0)
	s_barrier
	s_waitcnt lgkmcnt(0)
	v_mfma_f32_16x16x32_bf16 v[60:63], v[154:157], v[192:195], v[60:63]
	v_mfma_f32_16x16x32_bf16 v[52:55], v[162:165], v[192:195], v[52:55]
	v_mfma_f32_16x16x32_bf16 v[44:47], v[154:157], v[200:203], v[44:47]
	v_mfma_f32_16x16x32_bf16 v[36:39], v[162:165], v[200:203], v[36:39]
	v_mfma_f32_16x16x32_bf16 v[28:31], v[154:157], v[208:211], v[28:31]
	v_mfma_f32_16x16x32_bf16 v[20:23], v[162:165], v[208:211], v[20:23]
	v_mfma_f32_16x16x32_bf16 v[12:15], v[154:157], v[216:219], v[12:15]
	v_mfma_f32_16x16x32_bf16 v[4:7], v[162:165], v[216:219], v[4:7]
	v_mfma_f32_16x16x32_bf16 v[60:63], v[158:161], v[196:199], v[60:63]
	v_mfma_f32_16x16x32_bf16 v[52:55], v[166:169], v[196:199], v[52:55]
	v_mfma_f32_16x16x32_bf16 v[44:47], v[158:161], v[204:207], v[44:47]
	v_mfma_f32_16x16x32_bf16 v[36:39], v[166:169], v[204:207], v[36:39]
	v_mfma_f32_16x16x32_bf16 v[28:31], v[158:161], v[212:215], v[28:31]
	v_mfma_f32_16x16x32_bf16 v[20:23], v[166:169], v[212:215], v[20:23]
	v_mfma_f32_16x16x32_bf16 v[12:15], v[158:161], v[220:223], v[12:15]
	v_mfma_f32_16x16x32_bf16 v[4:7], v[166:169], v[220:223], v[4:7]
	v_mfma_f32_16x16x32_bf16 v[56:59], v[170:173], v[192:195], v[56:59]
	v_mfma_f32_16x16x32_bf16 v[48:51], v[184:187], v[192:195], v[48:51]
	v_mfma_f32_16x16x32_bf16 v[40:43], v[170:173], v[200:203], v[40:43]
	v_mfma_f32_16x16x32_bf16 v[32:35], v[184:187], v[200:203], v[32:35]
	v_mfma_f32_16x16x32_bf16 v[24:27], v[170:173], v[208:211], v[24:27]
	v_mfma_f32_16x16x32_bf16 v[16:19], v[184:187], v[208:211], v[16:19]
	v_mfma_f32_16x16x32_bf16 v[8:11], v[170:173], v[216:219], v[8:11]
	v_mfma_f32_16x16x32_bf16 v[0:3], v[184:187], v[216:219], v[0:3]
	v_mfma_f32_16x16x32_bf16 v[56:59], v[174:177], v[196:199], v[56:59]
	v_mfma_f32_16x16x32_bf16 v[48:51], v[188:191], v[196:199], v[48:51]
	v_mfma_f32_16x16x32_bf16 v[40:43], v[174:177], v[204:207], v[40:43]
	v_mfma_f32_16x16x32_bf16 v[32:35], v[188:191], v[204:207], v[32:35]
	v_mfma_f32_16x16x32_bf16 v[24:27], v[174:177], v[212:215], v[24:27]
	v_mfma_f32_16x16x32_bf16 v[16:19], v[188:191], v[212:215], v[16:19]
	s_setprio 3
	s_barrier
	v_mfma_f32_16x16x32_bf16 v[8:11], v[174:177], v[220:223], v[8:11]
	v_mfma_f32_16x16x32_bf16 v[0:3], v[188:191], v[220:223], v[0:3]
	s_setprio 0
	s_add_i32 s51, 0, 0x18000
	s_add_i32 s52, 0, 0x1c000
	v_add_u32_e32 v166, s51, v145
	v_add_u32_e32 v180, s52, v145
	ds_read_b128 v[154:157], v166
	ds_read_b128 v[158:161], v166 offset:1024
	ds_read_b128 v[162:165], v166 offset:2048
	ds_read_b128 v[166:169], v166 offset:3072
	ds_read_b128 v[170:173], v180
	ds_read_b128 v[174:177], v180 offset:1024
	ds_read_b128 v[184:187], v180 offset:2048
	ds_read_b128 v[188:191], v180 offset:3072
	v_lshl_add_u64 v[226:227], s[24:25], 0, v[134:135]
	s_mov_b32 m0, s19
	v_lshl_add_u64 v[228:229], s[24:25], 0, v[130:131]
	global_load_lds_dwordx4 v[226:227], off
	s_mov_b32 m0, s30
	s_nop 0
	global_load_lds_dwordx4 v[228:229], off
	s_add_u32 s24, s24, 0x40000
	s_addc_u32 s25, s25, 0
	s_mov_b32 m0, s31
	v_lshl_add_u64 v[230:231], s[24:25], 0, v[134:135]
	ds_read_b128 v[192:195], v153 offset:32768
	ds_read_b128 v[196:199], v153 offset:33792
	ds_read_b128 v[200:203], v153 offset:34816
	ds_read_b128 v[204:207], v153 offset:35840
	ds_read_b128 v[208:211], v153 offset:36864
	ds_read_b128 v[212:215], v153 offset:37888
	ds_read_b128 v[216:219], v153 offset:38912
	ds_read_b128 v[220:223], v153 offset:39936
	global_load_lds_dwordx4 v[230:231], off
	v_lshl_add_u64 v[230:231], s[24:25], 0, v[130:131]
	s_mov_b32 m0, s33
	s_nop 0
	global_load_lds_dwordx4 v[230:231], off
	s_waitcnt vmcnt(8)
	s_waitcnt lgkmcnt(0)
	s_barrier
	s_waitcnt lgkmcnt(0)
	v_mfma_f32_16x16x32_bf16 v[124:127], v[154:157], v[192:195], v[124:127]
	v_mfma_f32_16x16x32_bf16 v[116:119], v[162:165], v[192:195], v[116:119]
	v_mfma_f32_16x16x32_bf16 v[108:111], v[154:157], v[200:203], v[108:111]
	v_mfma_f32_16x16x32_bf16 v[100:103], v[162:165], v[200:203], v[100:103]
	v_mfma_f32_16x16x32_bf16 v[92:95], v[154:157], v[208:211], v[92:95]
	v_mfma_f32_16x16x32_bf16 v[84:87], v[162:165], v[208:211], v[84:87]
	v_mfma_f32_16x16x32_bf16 v[76:79], v[154:157], v[216:219], v[76:79]
	v_mfma_f32_16x16x32_bf16 v[68:71], v[162:165], v[216:219], v[68:71]
	v_mfma_f32_16x16x32_bf16 v[124:127], v[158:161], v[196:199], v[124:127]
	v_mfma_f32_16x16x32_bf16 v[116:119], v[166:169], v[196:199], v[116:119]
	v_mfma_f32_16x16x32_bf16 v[108:111], v[158:161], v[204:207], v[108:111]
	v_mfma_f32_16x16x32_bf16 v[100:103], v[166:169], v[204:207], v[100:103]
	v_mfma_f32_16x16x32_bf16 v[92:95], v[158:161], v[212:215], v[92:95]
	v_mfma_f32_16x16x32_bf16 v[84:87], v[166:169], v[212:215], v[84:87]
	v_mfma_f32_16x16x32_bf16 v[76:79], v[158:161], v[220:223], v[76:79]
	v_mfma_f32_16x16x32_bf16 v[68:71], v[166:169], v[220:223], v[68:71]
	v_mfma_f32_16x16x32_bf16 v[120:123], v[170:173], v[192:195], v[120:123]
	v_mfma_f32_16x16x32_bf16 v[112:115], v[184:187], v[192:195], v[112:115]
	v_mfma_f32_16x16x32_bf16 v[104:107], v[170:173], v[200:203], v[104:107]
	v_mfma_f32_16x16x32_bf16 v[96:99], v[184:187], v[200:203], v[96:99]
	v_mfma_f32_16x16x32_bf16 v[88:91], v[170:173], v[208:211], v[88:91]
	v_mfma_f32_16x16x32_bf16 v[80:83], v[184:187], v[208:211], v[80:83]
	v_mfma_f32_16x16x32_bf16 v[72:75], v[170:173], v[216:219], v[72:75]
	v_mfma_f32_16x16x32_bf16 v[64:67], v[184:187], v[216:219], v[64:67]
	v_mfma_f32_16x16x32_bf16 v[120:123], v[174:177], v[196:199], v[120:123]
	v_mfma_f32_16x16x32_bf16 v[112:115], v[188:191], v[196:199], v[112:115]
	v_mfma_f32_16x16x32_bf16 v[104:107], v[174:177], v[204:207], v[104:107]
	v_mfma_f32_16x16x32_bf16 v[96:99], v[188:191], v[204:207], v[96:99]
	v_mfma_f32_16x16x32_bf16 v[88:91], v[174:177], v[212:215], v[88:91]
	v_mfma_f32_16x16x32_bf16 v[80:83], v[188:191], v[212:215], v[80:83]
	s_setprio 3
	s_barrier
	v_mfma_f32_16x16x32_bf16 v[72:75], v[174:177], v[220:223], v[72:75]
	v_mfma_f32_16x16x32_bf16 v[64:67], v[188:191], v[220:223], v[64:67]
	s_setprio 0
	s_add_i32 s24, s51, s28
	v_lshl_add_u64 v[178:179], v[178:179], 0, s[6:7]
	s_mov_b32 m0, s24
	ds_read_b128 v[192:195], v153 offset:49152
	ds_read_b128 v[196:199], v153 offset:50176
	ds_read_b128 v[200:203], v153 offset:51200
	ds_read_b128 v[204:207], v153 offset:52224
	ds_read_b128 v[208:211], v153 offset:53248
	ds_read_b128 v[212:215], v153 offset:54272
	ds_read_b128 v[216:219], v153 offset:55296
	ds_read_b128 v[220:223], v153 offset:56320
	global_load_lds_dwordx4 v[178:179], off
	s_add_i32 m0, s24, 0x2000
	s_add_u32 s22, s22, 0x40080
	v_lshl_add_u64 v[178:179], v[224:225], 0, s[6:7]
	s_addc_u32 s23, s23, 0
	s_add_i32 s24, s52, s28
	global_load_lds_dwordx4 v[178:179], off
	v_lshl_add_u64 v[178:179], s[22:23], 0, v[132:133]
	s_mov_b32 m0, s24
	s_nop 0
	global_load_lds_dwordx4 v[178:179], off
	v_lshl_add_u64 v[178:179], s[22:23], 0, v[128:129]
	s_add_i32 m0, s24, 0x2000
	s_nop 0
	global_load_lds_dwordx4 v[178:179], off
	s_waitcnt vmcnt(6)
	s_waitcnt lgkmcnt(0)
	s_barrier
	s_waitcnt lgkmcnt(0)
	v_mfma_f32_16x16x32_bf16 v[60:63], v[154:157], v[192:195], v[60:63]
	v_mfma_f32_16x16x32_bf16 v[52:55], v[162:165], v[192:195], v[52:55]
	v_mfma_f32_16x16x32_bf16 v[44:47], v[154:157], v[200:203], v[44:47]
	v_mfma_f32_16x16x32_bf16 v[36:39], v[162:165], v[200:203], v[36:39]
	v_mfma_f32_16x16x32_bf16 v[28:31], v[154:157], v[208:211], v[28:31]
	v_mfma_f32_16x16x32_bf16 v[20:23], v[162:165], v[208:211], v[20:23]
	v_mfma_f32_16x16x32_bf16 v[12:15], v[154:157], v[216:219], v[12:15]
	v_mfma_f32_16x16x32_bf16 v[4:7], v[162:165], v[216:219], v[4:7]
	v_mfma_f32_16x16x32_bf16 v[60:63], v[158:161], v[196:199], v[60:63]
	v_mfma_f32_16x16x32_bf16 v[52:55], v[166:169], v[196:199], v[52:55]
	v_mfma_f32_16x16x32_bf16 v[44:47], v[158:161], v[204:207], v[44:47]
	v_mfma_f32_16x16x32_bf16 v[36:39], v[166:169], v[204:207], v[36:39]
	v_mfma_f32_16x16x32_bf16 v[28:31], v[158:161], v[212:215], v[28:31]
	v_mfma_f32_16x16x32_bf16 v[20:23], v[166:169], v[212:215], v[20:23]
	v_mfma_f32_16x16x32_bf16 v[12:15], v[158:161], v[220:223], v[12:15]
	v_mfma_f32_16x16x32_bf16 v[4:7], v[166:169], v[220:223], v[4:7]
	v_mfma_f32_16x16x32_bf16 v[56:59], v[170:173], v[192:195], v[56:59]
	v_mfma_f32_16x16x32_bf16 v[48:51], v[184:187], v[192:195], v[48:51]
	v_mfma_f32_16x16x32_bf16 v[40:43], v[170:173], v[200:203], v[40:43]
	v_mfma_f32_16x16x32_bf16 v[32:35], v[184:187], v[200:203], v[32:35]
	v_mfma_f32_16x16x32_bf16 v[24:27], v[170:173], v[208:211], v[24:27]
	v_mfma_f32_16x16x32_bf16 v[16:19], v[184:187], v[208:211], v[16:19]
	v_mfma_f32_16x16x32_bf16 v[8:11], v[170:173], v[216:219], v[8:11]
	v_mfma_f32_16x16x32_bf16 v[0:3], v[184:187], v[216:219], v[0:3]
	v_mfma_f32_16x16x32_bf16 v[56:59], v[174:177], v[196:199], v[56:59]
	v_mfma_f32_16x16x32_bf16 v[48:51], v[188:191], v[196:199], v[48:51]
	v_mfma_f32_16x16x32_bf16 v[40:43], v[174:177], v[204:207], v[40:43]
	v_mfma_f32_16x16x32_bf16 v[32:35], v[188:191], v[204:207], v[32:35]
	v_mfma_f32_16x16x32_bf16 v[24:27], v[174:177], v[212:215], v[24:27]
	v_mfma_f32_16x16x32_bf16 v[16:19], v[188:191], v[212:215], v[16:19]
	s_setprio 3
	s_barrier
	v_mfma_f32_16x16x32_bf16 v[8:11], v[174:177], v[220:223], v[8:11]
	v_mfma_f32_16x16x32_bf16 v[0:3], v[188:191], v[220:223], v[0:3]
	s_setprio 0
	v_lshl_add_u64 v[178:179], v[226:227], 0, s[6:7]
	s_mov_b32 m0, s34
	s_nop 0
	global_load_lds_dwordx4 v[178:179], off
	v_lshl_add_u64 v[178:179], v[228:229], 0, s[6:7]
	s_mov_b32 m0, s35
	s_nop 0
	global_load_lds_dwordx4 v[178:179], off
	s_add_i32 s50, s50, 2
	s_add_u32 s20, s20, 0x100
	s_addc_u32 s21, s21, 0
	s_add_u32 s46, s46, 0x100
	s_addc_u32 s47, s47, 0
	s_cmp_gt_u32 s50, 13
	s_cbranch_scc0 .LBB0_705
	s_and_b64 vcc, exec, s[8:9]
	s_cbranch_vccz .LBB0_708
	s_barrier

.LBB0_787:
	ds_read_b128 v[144:147], v151
	ds_read_b128 v[156:159], v151 offset:1024
	ds_read_b128 v[160:163], v151 offset:2048
	ds_read_b128 v[164:167], v151 offset:3072
	ds_read_b128 v[168:171], v152
	ds_read_b128 v[172:175], v152 offset:1024
	ds_read_b128 v[176:179], v152 offset:2048
	ds_read_b128 v[184:187], v152 offset:3072
	s_add_u32 s20, s18, 0x100
	s_addc_u32 s21, s19, 0
	s_cmp_eq_u32 s47, 40
	s_cselect_b32 s25, s7, s21
	s_cselect_b32 s24, s6, s20
	s_cselect_b32 s23, s17, s46
	s_cselect_b32 s22, s16, s43
	v_lshl_add_u64 v[220:221], s[18:19], 0, v[136:137]
	s_add_i32 m0, s29, 0xc000
	ds_read_b128 v[188:191], v153
	ds_read_b128 v[192:195], v153 offset:1024
	ds_read_b128 v[196:199], v153 offset:2048
	ds_read_b128 v[200:203], v153 offset:3072
	ds_read_b128 v[204:207], v153 offset:4096
	ds_read_b128 v[208:211], v153 offset:5120
	ds_read_b128 v[212:215], v153 offset:6144
	ds_read_b128 v[216:219], v153 offset:7168
	global_load_lds_dwordx4 v[220:221], off
	v_lshl_add_u64 v[220:221], s[18:19], 0, v[138:139]
	s_add_i32 m0, s29, 0xe000
	s_nop 0
	global_load_lds_dwordx4 v[220:221], off
	s_waitcnt vmcnt(8)
	s_waitcnt lgkmcnt(0)
	s_barrier
	s_waitcnt lgkmcnt(0)
	v_mfma_f32_16x16x32_bf16 v[124:127], v[144:147], v[188:191], v[124:127]
	v_mfma_f32_16x16x32_bf16 v[120:123], v[160:163], v[188:191], v[120:123]
	v_mfma_f32_16x16x32_bf16 v[108:111], v[144:147], v[196:199], v[108:111]
	v_mfma_f32_16x16x32_bf16 v[104:107], v[160:163], v[196:199], v[104:107]
	v_mfma_f32_16x16x32_bf16 v[92:95], v[144:147], v[204:207], v[92:95]
	v_mfma_f32_16x16x32_bf16 v[88:91], v[160:163], v[204:207], v[88:91]
	v_mfma_f32_16x16x32_bf16 v[76:79], v[144:147], v[212:215], v[76:79]
	v_mfma_f32_16x16x32_bf16 v[72:75], v[160:163], v[212:215], v[72:75]
	v_mfma_f32_16x16x32_bf16 v[124:127], v[156:159], v[192:195], v[124:127]
	v_mfma_f32_16x16x32_bf16 v[120:123], v[164:167], v[192:195], v[120:123]
	v_mfma_f32_16x16x32_bf16 v[108:111], v[156:159], v[200:203], v[108:111]
	v_mfma_f32_16x16x32_bf16 v[104:107], v[164:167], v[200:203], v[104:107]
	v_mfma_f32_16x16x32_bf16 v[92:95], v[156:159], v[208:211], v[92:95]
	v_mfma_f32_16x16x32_bf16 v[88:91], v[164:167], v[208:211], v[88:91]
	v_mfma_f32_16x16x32_bf16 v[76:79], v[156:159], v[216:219], v[76:79]
	v_mfma_f32_16x16x32_bf16 v[72:75], v[164:167], v[216:219], v[72:75]
	v_mfma_f32_16x16x32_bf16 v[116:119], v[168:171], v[188:191], v[116:119]
	v_mfma_f32_16x16x32_bf16 v[112:115], v[176:179], v[188:191], v[112:115]
	v_mfma_f32_16x16x32_bf16 v[100:103], v[168:171], v[196:199], v[100:103]
	v_mfma_f32_16x16x32_bf16 v[96:99], v[176:179], v[196:199], v[96:99]
	v_mfma_f32_16x16x32_bf16 v[84:87], v[168:171], v[204:207], v[84:87]
	v_mfma_f32_16x16x32_bf16 v[80:83], v[176:179], v[204:207], v[80:83]
	v_mfma_f32_16x16x32_bf16 v[68:71], v[168:171], v[212:215], v[68:71]
	v_mfma_f32_16x16x32_bf16 v[64:67], v[176:179], v[212:215], v[64:67]
	v_mfma_f32_16x16x32_bf16 v[116:119], v[172:175], v[192:195], v[116:119]
	v_mfma_f32_16x16x32_bf16 v[112:115], v[184:187], v[192:195], v[112:115]
	v_mfma_f32_16x16x32_bf16 v[100:103], v[172:175], v[200:203], v[100:103]
	v_mfma_f32_16x16x32_bf16 v[96:99], v[184:187], v[200:203], v[96:99]
	v_mfma_f32_16x16x32_bf16 v[84:87], v[172:175], v[208:211], v[84:87]
	v_mfma_f32_16x16x32_bf16 v[80:83], v[184:187], v[208:211], v[80:83]
	s_setprio 3
	s_barrier
	v_mfma_f32_16x16x32_bf16 v[68:71], v[172:175], v[216:219], v[68:71]
	v_mfma_f32_16x16x32_bf16 v[64:67], v[184:187], v[216:219], v[64:67]
	s_setprio 0
	s_add_i32 s18, s37, s28
	v_lshl_add_u64 v[220:221], s[22:23], 0, v[130:131]
	s_mov_b32 m0, s18
	ds_read_b128 v[188:191], v153 offset:16384
	ds_read_b128 v[192:195], v153 offset:17408
	ds_read_b128 v[196:199], v153 offset:18432
	ds_read_b128 v[200:203], v153 offset:19456
	ds_read_b128 v[204:207], v153 offset:20480
	ds_read_b128 v[208:211], v153 offset:21504
	ds_read_b128 v[212:215], v153 offset:22528
	ds_read_b128 v[216:219], v153 offset:23552
	global_load_lds_dwordx4 v[220:221], off
	s_add_i32 m0, s18, 0x2000
	s_add_u32 s18, s22, 0xb0000
	v_lshl_add_u64 v[222:223], s[22:23], 0, v[134:135]
	s_addc_u32 s19, s23, 0
	s_add_i32 s50, s38, s28
	global_load_lds_dwordx4 v[222:223], off
	v_lshl_add_u64 v[224:225], s[18:19], 0, v[130:131]
	s_mov_b32 m0, s50
	global_load_lds_dwordx4 v[224:225], off
	v_lshl_add_u64 v[224:225], s[18:19], 0, v[134:135]
	s_add_i32 m0, s50, 0x2000
	s_nop 0
	global_load_lds_dwordx4 v[224:225], off
	s_waitcnt vmcnt(6)
	s_waitcnt lgkmcnt(0)
	s_barrier
	s_waitcnt lgkmcnt(0)
	v_mfma_f32_16x16x32_bf16 v[60:63], v[144:147], v[188:191], v[60:63]
	v_mfma_f32_16x16x32_bf16 v[56:59], v[160:163], v[188:191], v[56:59]
	v_mfma_f32_16x16x32_bf16 v[44:47], v[144:147], v[196:199], v[44:47]
	v_mfma_f32_16x16x32_bf16 v[40:43], v[160:163], v[196:199], v[40:43]
	v_mfma_f32_16x16x32_bf16 v[28:31], v[144:147], v[204:207], v[28:31]
	v_mfma_f32_16x16x32_bf16 v[24:27], v[160:163], v[204:207], v[24:27]
	v_mfma_f32_16x16x32_bf16 v[12:15], v[144:147], v[212:215], v[12:15]
	v_mfma_f32_16x16x32_bf16 v[8:11], v[160:163], v[212:215], v[8:11]
	v_mfma_f32_16x16x32_bf16 v[60:63], v[156:159], v[192:195], v[60:63]
	v_mfma_f32_16x16x32_bf16 v[56:59], v[164:167], v[192:195], v[56:59]
	v_mfma_f32_16x16x32_bf16 v[44:47], v[156:159], v[200:203], v[44:47]
	v_mfma_f32_16x16x32_bf16 v[40:43], v[164:167], v[200:203], v[40:43]
	v_mfma_f32_16x16x32_bf16 v[28:31], v[156:159], v[208:211], v[28:31]
	v_mfma_f32_16x16x32_bf16 v[24:27], v[164:167], v[208:211], v[24:27]
	v_mfma_f32_16x16x32_bf16 v[12:15], v[156:159], v[216:219], v[12:15]
	v_mfma_f32_16x16x32_bf16 v[8:11], v[164:167], v[216:219], v[8:11]
	v_mfma_f32_16x16x32_bf16 v[52:55], v[168:171], v[188:191], v[52:55]
	v_mfma_f32_16x16x32_bf16 v[48:51], v[176:179], v[188:191], v[48:51]
	v_mfma_f32_16x16x32_bf16 v[36:39], v[168:171], v[196:199], v[36:39]
	v_mfma_f32_16x16x32_bf16 v[32:35], v[176:179], v[196:199], v[32:35]
	v_mfma_f32_16x16x32_bf16 v[20:23], v[168:171], v[204:207], v[20:23]
	v_mfma_f32_16x16x32_bf16 v[16:19], v[176:179], v[204:207], v[16:19]
	v_mfma_f32_16x16x32_bf16 v[4:7], v[168:171], v[212:215], v[4:7]
	v_mfma_f32_16x16x32_bf16 v[0:3], v[176:179], v[212:215], v[0:3]
	v_mfma_f32_16x16x32_bf16 v[52:55], v[172:175], v[192:195], v[52:55]
	v_mfma_f32_16x16x32_bf16 v[48:51], v[184:187], v[192:195], v[48:51]
	v_mfma_f32_16x16x32_bf16 v[36:39], v[172:175], v[200:203], v[36:39]
	v_mfma_f32_16x16x32_bf16 v[32:35], v[184:187], v[200:203], v[32:35]
	v_mfma_f32_16x16x32_bf16 v[20:23], v[172:175], v[208:211], v[20:23]
	v_mfma_f32_16x16x32_bf16 v[16:19], v[184:187], v[208:211], v[16:19]
	s_setprio 3
	s_barrier
	v_mfma_f32_16x16x32_bf16 v[4:7], v[172:175], v[216:219], v[4:7]
	v_mfma_f32_16x16x32_bf16 v[0:3], v[184:187], v[216:219], v[0:3]
	s_setprio 0
	s_add_i32 s50, 0, 0x18000
	v_add_u32_e32 v155, s50, v149
	s_add_i32 s51, 0, 0x1c000
	ds_read_b128 v[144:147], v155
	ds_read_b128 v[156:159], v155 offset:1024
	ds_read_b128 v[160:163], v155 offset:2048
	ds_read_b128 v[164:167], v155 offset:3072
	v_add_u32_e32 v155, s51, v149
	ds_read_b128 v[168:171], v155
	ds_read_b128 v[172:175], v155 offset:1024
	ds_read_b128 v[176:179], v155 offset:2048
	ds_read_b128 v[184:187], v155 offset:3072
	s_add_u32 s18, s24, 0xb0000
	s_addc_u32 s19, s25, 0
	v_lshl_add_u64 v[224:225], s[24:25], 0, v[128:129]
	s_mov_b32 m0, s29
	v_lshl_add_u64 v[226:227], s[24:25], 0, v[132:133]
	global_load_lds_dwordx4 v[224:225], off
	s_mov_b32 m0, s30
	s_nop 0
	global_load_lds_dwordx4 v[226:227], off
	s_mov_b32 m0, s31
	v_lshl_add_u64 v[228:229], s[18:19], 0, v[128:129]
	ds_read_b128 v[188:191], v153 offset:32768
	ds_read_b128 v[192:195], v153 offset:33792
	ds_read_b128 v[196:199], v153 offset:34816
	ds_read_b128 v[200:203], v153 offset:35840
	ds_read_b128 v[204:207], v153 offset:36864
	ds_read_b128 v[208:211], v153 offset:37888
	ds_read_b128 v[212:215], v153 offset:38912
	ds_read_b128 v[216:219], v153 offset:39936
	global_load_lds_dwordx4 v[228:229], off
	v_lshl_add_u64 v[228:229], s[18:19], 0, v[132:133]
	s_mov_b32 m0, s33
	s_nop 0
	global_load_lds_dwordx4 v[228:229], off
	s_waitcnt vmcnt(8)
	s_waitcnt lgkmcnt(0)
	s_barrier
	s_waitcnt lgkmcnt(0)
	v_mfma_f32_16x16x32_bf16 v[124:127], v[144:147], v[188:191], v[124:127]
	v_mfma_f32_16x16x32_bf16 v[120:123], v[160:163], v[188:191], v[120:123]
	v_mfma_f32_16x16x32_bf16 v[108:111], v[144:147], v[196:199], v[108:111]
	v_mfma_f32_16x16x32_bf16 v[104:107], v[160:163], v[196:199], v[104:107]
	v_mfma_f32_16x16x32_bf16 v[92:95], v[144:147], v[204:207], v[92:95]
	v_mfma_f32_16x16x32_bf16 v[88:91], v[160:163], v[204:207], v[88:91]
	v_mfma_f32_16x16x32_bf16 v[76:79], v[144:147], v[212:215], v[76:79]
	v_mfma_f32_16x16x32_bf16 v[72:75], v[160:163], v[212:215], v[72:75]
	v_mfma_f32_16x16x32_bf16 v[124:127], v[156:159], v[192:195], v[124:127]
	v_mfma_f32_16x16x32_bf16 v[120:123], v[164:167], v[192:195], v[120:123]
	v_mfma_f32_16x16x32_bf16 v[108:111], v[156:159], v[200:203], v[108:111]
	v_mfma_f32_16x16x32_bf16 v[104:107], v[164:167], v[200:203], v[104:107]
	v_mfma_f32_16x16x32_bf16 v[92:95], v[156:159], v[208:211], v[92:95]
	v_mfma_f32_16x16x32_bf16 v[88:91], v[164:167], v[208:211], v[88:91]
	v_mfma_f32_16x16x32_bf16 v[76:79], v[156:159], v[216:219], v[76:79]
	v_mfma_f32_16x16x32_bf16 v[72:75], v[164:167], v[216:219], v[72:75]
	v_mfma_f32_16x16x32_bf16 v[116:119], v[168:171], v[188:191], v[116:119]
	v_mfma_f32_16x16x32_bf16 v[112:115], v[176:179], v[188:191], v[112:115]
	v_mfma_f32_16x16x32_bf16 v[100:103], v[168:171], v[196:199], v[100:103]
	v_mfma_f32_16x16x32_bf16 v[96:99], v[176:179], v[196:199], v[96:99]
	v_mfma_f32_16x16x32_bf16 v[84:87], v[168:171], v[204:207], v[84:87]
	v_mfma_f32_16x16x32_bf16 v[80:83], v[176:179], v[204:207], v[80:83]
	v_mfma_f32_16x16x32_bf16 v[68:71], v[168:171], v[212:215], v[68:71]
	v_mfma_f32_16x16x32_bf16 v[64:67], v[176:179], v[212:215], v[64:67]
	v_mfma_f32_16x16x32_bf16 v[116:119], v[172:175], v[192:195], v[116:119]
	v_mfma_f32_16x16x32_bf16 v[112:115], v[184:187], v[192:195], v[112:115]
	v_mfma_f32_16x16x32_bf16 v[100:103], v[172:175], v[200:203], v[100:103]
	v_mfma_f32_16x16x32_bf16 v[96:99], v[184:187], v[200:203], v[96:99]
	v_mfma_f32_16x16x32_bf16 v[84:87], v[172:175], v[208:211], v[84:87]
	v_mfma_f32_16x16x32_bf16 v[80:83], v[184:187], v[208:211], v[80:83]
	s_setprio 3
	s_barrier
	v_mfma_f32_16x16x32_bf16 v[68:71], v[172:175], v[216:219], v[68:71]
	v_mfma_f32_16x16x32_bf16 v[64:67], v[184:187], v[216:219], v[64:67]
	s_setprio 0
	s_add_i32 s18, s50, s28
	v_lshl_add_u64 v[220:221], v[220:221], 0, s[12:13]
	s_mov_b32 m0, s18
	ds_read_b128 v[188:191], v153 offset:49152
	ds_read_b128 v[192:195], v153 offset:50176
	ds_read_b128 v[196:199], v153 offset:51200
	ds_read_b128 v[200:203], v153 offset:52224
	ds_read_b128 v[204:207], v153 offset:53248
	ds_read_b128 v[208:211], v153 offset:54272
	ds_read_b128 v[212:215], v153 offset:55296
	ds_read_b128 v[216:219], v153 offset:56320
	global_load_lds_dwordx4 v[220:221], off
	s_add_i32 m0, s18, 0x2000
	s_add_u32 s18, s22, 0xb0080
	v_lshl_add_u64 v[220:221], v[222:223], 0, s[12:13]
	s_addc_u32 s19, s23, 0
	s_add_i32 s22, s51, s28
	global_load_lds_dwordx4 v[220:221], off
	v_lshl_add_u64 v[220:221], s[18:19], 0, v[130:131]
	s_mov_b32 m0, s22
	s_nop 0
	global_load_lds_dwordx4 v[220:221], off
	v_lshl_add_u64 v[220:221], s[18:19], 0, v[134:135]
	s_add_i32 m0, s22, 0x2000
	s_nop 0
	global_load_lds_dwordx4 v[220:221], off
	s_waitcnt vmcnt(6)
	s_waitcnt lgkmcnt(0)
	s_barrier
	s_waitcnt lgkmcnt(0)
	v_mfma_f32_16x16x32_bf16 v[60:63], v[144:147], v[188:191], v[60:63]
	v_mfma_f32_16x16x32_bf16 v[56:59], v[160:163], v[188:191], v[56:59]
	v_mfma_f32_16x16x32_bf16 v[44:47], v[144:147], v[196:199], v[44:47]
	v_mfma_f32_16x16x32_bf16 v[40:43], v[160:163], v[196:199], v[40:43]
	v_mfma_f32_16x16x32_bf16 v[28:31], v[144:147], v[204:207], v[28:31]
	v_mfma_f32_16x16x32_bf16 v[24:27], v[160:163], v[204:207], v[24:27]
	v_mfma_f32_16x16x32_bf16 v[12:15], v[144:147], v[212:215], v[12:15]
	v_mfma_f32_16x16x32_bf16 v[8:11], v[160:163], v[212:215], v[8:11]
	v_mfma_f32_16x16x32_bf16 v[60:63], v[156:159], v[192:195], v[60:63]
	v_mfma_f32_16x16x32_bf16 v[56:59], v[164:167], v[192:195], v[56:59]
	v_mfma_f32_16x16x32_bf16 v[44:47], v[156:159], v[200:203], v[44:47]
	v_mfma_f32_16x16x32_bf16 v[40:43], v[164:167], v[200:203], v[40:43]
	v_mfma_f32_16x16x32_bf16 v[28:31], v[156:159], v[208:211], v[28:31]
	v_mfma_f32_16x16x32_bf16 v[24:27], v[164:167], v[208:211], v[24:27]
	v_mfma_f32_16x16x32_bf16 v[12:15], v[156:159], v[216:219], v[12:15]
	v_mfma_f32_16x16x32_bf16 v[8:11], v[164:167], v[216:219], v[8:11]
	v_mfma_f32_16x16x32_bf16 v[52:55], v[168:171], v[188:191], v[52:55]
	v_mfma_f32_16x16x32_bf16 v[48:51], v[176:179], v[188:191], v[48:51]
	v_mfma_f32_16x16x32_bf16 v[36:39], v[168:171], v[196:199], v[36:39]
	v_mfma_f32_16x16x32_bf16 v[32:35], v[176:179], v[196:199], v[32:35]
	v_mfma_f32_16x16x32_bf16 v[20:23], v[168:171], v[204:207], v[20:23]
	v_mfma_f32_16x16x32_bf16 v[16:19], v[176:179], v[204:207], v[16:19]
	v_mfma_f32_16x16x32_bf16 v[4:7], v[168:171], v[212:215], v[4:7]
	v_mfma_f32_16x16x32_bf16 v[0:3], v[176:179], v[212:215], v[0:3]
	v_mfma_f32_16x16x32_bf16 v[52:55], v[172:175], v[192:195], v[52:55]
	v_mfma_f32_16x16x32_bf16 v[48:51], v[184:187], v[192:195], v[48:51]
	v_mfma_f32_16x16x32_bf16 v[36:39], v[172:175], v[200:203], v[36:39]
	v_mfma_f32_16x16x32_bf16 v[32:35], v[184:187], v[200:203], v[32:35]
	v_mfma_f32_16x16x32_bf16 v[20:23], v[172:175], v[208:211], v[20:23]
	v_mfma_f32_16x16x32_bf16 v[16:19], v[184:187], v[208:211], v[16:19]
	s_setprio 3
	s_barrier
	v_mfma_f32_16x16x32_bf16 v[4:7], v[172:175], v[216:219], v[4:7]
	v_mfma_f32_16x16x32_bf16 v[0:3], v[184:187], v[216:219], v[0:3]
	s_setprio 0
	v_lshl_add_u64 v[220:221], v[224:225], 0, s[12:13]
	s_mov_b32 m0, s35
	s_nop 0
	global_load_lds_dwordx4 v[220:221], off
	v_lshl_add_u64 v[220:221], v[226:227], 0, s[12:13]
	s_mov_b32 m0, s36
	s_nop 0
	global_load_lds_dwordx4 v[220:221], off
	s_add_i32 s47, s47, 2
	s_add_u32 s43, s43, 0x100
	s_addc_u32 s46, s46, 0
	s_cmp_gt_u32 s47, 41
	s_mov_b64 s[18:19], s[20:21]
	s_cbranch_scc0 .LBB0_787
	s_and_b64 vcc, exec, s[14:15]
	s_cbranch_vccz .LBB0_790
	s_barrier

.LBB0_877:
	ds_read_b128 v[144:147], v173
	ds_read_b128 v[148:151], v173 offset:1024
	ds_read_b128 v[152:155], v173 offset:2048
	ds_read_b128 v[156:159], v173 offset:3072
	ds_read_b128 v[184:187], v174
	ds_read_b128 v[188:191], v174 offset:1024
	ds_read_b128 v[192:195], v174 offset:2048
	ds_read_b128 v[196:199], v174 offset:3072
	s_add_u32 s30, s28, 0xfffc0080
	s_addc_u32 s31, s29, -1
	s_cmp_eq_u32 s56, 12
	s_cselect_b32 s35, s11, s31
	s_cselect_b32 s34, s23, s30
	s_cselect_b32 s31, s21, s55
	s_cselect_b32 s30, s53, s54
	v_lshl_add_u64 v[160:161], s[28:29], 0, v[136:137]
	s_add_i32 m0, s38, 0xc000
	ds_read_b128 v[200:203], v175
	ds_read_b128 v[204:207], v175 offset:1024
	ds_read_b128 v[208:211], v175 offset:2048
	ds_read_b128 v[212:215], v175 offset:3072
	ds_read_b128 v[216:219], v175 offset:4096
	ds_read_b128 v[220:223], v175 offset:5120
	ds_read_b128 v[224:227], v175 offset:6144
	ds_read_b128 v[228:231], v175 offset:7168
	global_load_lds_dwordx4 v[160:161], off
	v_lshl_add_u64 v[160:161], s[28:29], 0, v[138:139]
	s_add_i32 m0, s38, 0xe000
	s_nop 0
	global_load_lds_dwordx4 v[160:161], off
	s_waitcnt vmcnt(8)
	s_waitcnt lgkmcnt(0)
	s_barrier
	s_waitcnt lgkmcnt(0)
	v_mfma_f32_16x16x32_bf16 v[124:127], v[144:147], v[200:203], v[124:127]
	v_mfma_f32_16x16x32_bf16 v[120:123], v[152:155], v[200:203], v[120:123]
	v_mfma_f32_16x16x32_bf16 v[108:111], v[144:147], v[208:211], v[108:111]
	v_mfma_f32_16x16x32_bf16 v[104:107], v[152:155], v[208:211], v[104:107]
	v_mfma_f32_16x16x32_bf16 v[92:95], v[144:147], v[216:219], v[92:95]
	v_mfma_f32_16x16x32_bf16 v[88:91], v[152:155], v[216:219], v[88:91]
	v_mfma_f32_16x16x32_bf16 v[76:79], v[144:147], v[224:227], v[76:79]
	v_mfma_f32_16x16x32_bf16 v[72:75], v[152:155], v[224:227], v[72:75]
	v_mfma_f32_16x16x32_bf16 v[124:127], v[148:151], v[204:207], v[124:127]
	v_mfma_f32_16x16x32_bf16 v[120:123], v[156:159], v[204:207], v[120:123]
	v_mfma_f32_16x16x32_bf16 v[108:111], v[148:151], v[212:215], v[108:111]
	v_mfma_f32_16x16x32_bf16 v[104:107], v[156:159], v[212:215], v[104:107]
	v_mfma_f32_16x16x32_bf16 v[92:95], v[148:151], v[220:223], v[92:95]
	v_mfma_f32_16x16x32_bf16 v[88:91], v[156:159], v[220:223], v[88:91]
	v_mfma_f32_16x16x32_bf16 v[76:79], v[148:151], v[228:231], v[76:79]
	v_mfma_f32_16x16x32_bf16 v[72:75], v[156:159], v[228:231], v[72:75]
	v_mfma_f32_16x16x32_bf16 v[116:119], v[184:187], v[200:203], v[116:119]
	v_mfma_f32_16x16x32_bf16 v[112:115], v[192:195], v[200:203], v[112:115]
	v_mfma_f32_16x16x32_bf16 v[100:103], v[184:187], v[208:211], v[100:103]
	v_mfma_f32_16x16x32_bf16 v[96:99], v[192:195], v[208:211], v[96:99]
	v_mfma_f32_16x16x32_bf16 v[84:87], v[184:187], v[216:219], v[84:87]
	v_mfma_f32_16x16x32_bf16 v[80:83], v[192:195], v[216:219], v[80:83]
	v_mfma_f32_16x16x32_bf16 v[68:71], v[184:187], v[224:227], v[68:71]
	v_mfma_f32_16x16x32_bf16 v[64:67], v[192:195], v[224:227], v[64:67]
	v_mfma_f32_16x16x32_bf16 v[116:119], v[188:191], v[204:207], v[116:119]
	v_mfma_f32_16x16x32_bf16 v[112:115], v[196:199], v[204:207], v[112:115]
	v_mfma_f32_16x16x32_bf16 v[100:103], v[188:191], v[212:215], v[100:103]
	v_mfma_f32_16x16x32_bf16 v[96:99], v[196:199], v[212:215], v[96:99]
	v_mfma_f32_16x16x32_bf16 v[84:87], v[188:191], v[220:223], v[84:87]
	v_mfma_f32_16x16x32_bf16 v[80:83], v[196:199], v[220:223], v[80:83]
	s_setprio 3
	s_barrier
	v_mfma_f32_16x16x32_bf16 v[68:71], v[188:191], v[228:231], v[68:71]
	v_mfma_f32_16x16x32_bf16 v[64:67], v[196:199], v[228:231], v[64:67]
	s_setprio 0
	s_add_i32 s57, s47, s37
	v_lshl_add_u64 v[160:161], s[30:31], 0, v[130:131]
	s_mov_b32 m0, s57
	ds_read_b128 v[200:203], v175 offset:16384
	ds_read_b128 v[204:207], v175 offset:17408
	ds_read_b128 v[208:211], v175 offset:18432
	ds_read_b128 v[212:215], v175 offset:19456
	ds_read_b128 v[216:219], v175 offset:20480
	ds_read_b128 v[220:223], v175 offset:21504
	ds_read_b128 v[224:227], v175 offset:22528
	ds_read_b128 v[228:231], v175 offset:23552
	global_load_lds_dwordx4 v[160:161], off
	s_add_i32 m0, s57, 0x2000
	s_add_u32 s58, s30, 0x40000
	v_lshl_add_u64 v[178:179], s[30:31], 0, v[134:135]
	s_addc_u32 s59, s31, 0
	s_add_i32 s57, s50, s37
	global_load_lds_dwordx4 v[178:179], off
	v_lshl_add_u64 v[232:233], s[58:59], 0, v[130:131]
	s_mov_b32 m0, s57
	global_load_lds_dwordx4 v[232:233], off
	v_lshl_add_u64 v[232:233], s[58:59], 0, v[134:135]
	s_add_i32 m0, s57, 0x2000
	s_nop 0
	global_load_lds_dwordx4 v[232:233], off
	s_waitcnt vmcnt(6)
	s_waitcnt lgkmcnt(0)
	s_barrier
	s_waitcnt lgkmcnt(0)
	v_mfma_f32_16x16x32_bf16 v[60:63], v[144:147], v[200:203], v[60:63]
	v_mfma_f32_16x16x32_bf16 v[56:59], v[152:155], v[200:203], v[56:59]
	v_mfma_f32_16x16x32_bf16 v[44:47], v[144:147], v[208:211], v[44:47]
	v_mfma_f32_16x16x32_bf16 v[40:43], v[152:155], v[208:211], v[40:43]
	v_mfma_f32_16x16x32_bf16 v[28:31], v[144:147], v[216:219], v[28:31]
	v_mfma_f32_16x16x32_bf16 v[24:27], v[152:155], v[216:219], v[24:27]
	v_mfma_f32_16x16x32_bf16 v[12:15], v[144:147], v[224:227], v[12:15]
	v_mfma_f32_16x16x32_bf16 v[8:11], v[152:155], v[224:227], v[8:11]
	v_mfma_f32_16x16x32_bf16 v[60:63], v[148:151], v[204:207], v[60:63]
	v_mfma_f32_16x16x32_bf16 v[56:59], v[156:159], v[204:207], v[56:59]
	v_mfma_f32_16x16x32_bf16 v[44:47], v[148:151], v[212:215], v[44:47]
	v_mfma_f32_16x16x32_bf16 v[40:43], v[156:159], v[212:215], v[40:43]
	v_mfma_f32_16x16x32_bf16 v[28:31], v[148:151], v[220:223], v[28:31]
	v_mfma_f32_16x16x32_bf16 v[24:27], v[156:159], v[220:223], v[24:27]
	v_mfma_f32_16x16x32_bf16 v[12:15], v[148:151], v[228:231], v[12:15]
	v_mfma_f32_16x16x32_bf16 v[8:11], v[156:159], v[228:231], v[8:11]
	v_mfma_f32_16x16x32_bf16 v[52:55], v[184:187], v[200:203], v[52:55]
	v_mfma_f32_16x16x32_bf16 v[48:51], v[192:195], v[200:203], v[48:51]
	v_mfma_f32_16x16x32_bf16 v[36:39], v[184:187], v[208:211], v[36:39]
	v_mfma_f32_16x16x32_bf16 v[32:35], v[192:195], v[208:211], v[32:35]
	v_mfma_f32_16x16x32_bf16 v[20:23], v[184:187], v[216:219], v[20:23]
	v_mfma_f32_16x16x32_bf16 v[16:19], v[192:195], v[216:219], v[16:19]
	v_mfma_f32_16x16x32_bf16 v[4:7], v[184:187], v[224:227], v[4:7]
	v_mfma_f32_16x16x32_bf16 v[0:3], v[192:195], v[224:227], v[0:3]
	v_mfma_f32_16x16x32_bf16 v[52:55], v[188:191], v[204:207], v[52:55]
	v_mfma_f32_16x16x32_bf16 v[48:51], v[196:199], v[204:207], v[48:51]
	v_mfma_f32_16x16x32_bf16 v[36:39], v[188:191], v[212:215], v[36:39]
	v_mfma_f32_16x16x32_bf16 v[32:35], v[196:199], v[212:215], v[32:35]
	v_mfma_f32_16x16x32_bf16 v[20:23], v[188:191], v[220:223], v[20:23]
	v_mfma_f32_16x16x32_bf16 v[16:19], v[196:199], v[220:223], v[16:19]
	s_setprio 3
	s_barrier
	v_mfma_f32_16x16x32_bf16 v[4:7], v[188:191], v[228:231], v[4:7]
	v_mfma_f32_16x16x32_bf16 v[0:3], v[196:199], v[228:231], v[0:3]
	s_setprio 0
	s_add_i32 s57, 0, 0x18000
	s_add_i32 s58, 0, 0x1c000
	v_add_u32_e32 v156, s57, v163
	v_add_u32_e32 v177, s58, v163
	ds_read_b128 v[144:147], v156
	ds_read_b128 v[148:151], v156 offset:1024
	ds_read_b128 v[152:155], v156 offset:2048
	ds_read_b128 v[156:159], v156 offset:3072
	ds_read_b128 v[184:187], v177
	ds_read_b128 v[188:191], v177 offset:1024
	ds_read_b128 v[192:195], v177 offset:2048
	ds_read_b128 v[196:199], v177 offset:3072
	v_lshl_add_u64 v[232:233], s[34:35], 0, v[128:129]
	s_mov_b32 m0, s38
	v_lshl_add_u64 v[234:235], s[34:35], 0, v[132:133]
	global_load_lds_dwordx4 v[232:233], off
	s_mov_b32 m0, s39
	s_nop 0
	global_load_lds_dwordx4 v[234:235], off
	s_add_u32 s34, s34, 0x40000
	s_addc_u32 s35, s35, 0
	s_mov_b32 m0, s40
	v_lshl_add_u64 v[236:237], s[34:35], 0, v[128:129]
	ds_read_b128 v[200:203], v175 offset:32768
	ds_read_b128 v[204:207], v175 offset:33792
	ds_read_b128 v[208:211], v175 offset:34816
	ds_read_b128 v[212:215], v175 offset:35840
	ds_read_b128 v[216:219], v175 offset:36864
	ds_read_b128 v[220:223], v175 offset:37888
	ds_read_b128 v[224:227], v175 offset:38912
	ds_read_b128 v[228:231], v175 offset:39936
	global_load_lds_dwordx4 v[236:237], off
	v_lshl_add_u64 v[236:237], s[34:35], 0, v[132:133]
	s_mov_b32 m0, s41
	s_nop 0
	global_load_lds_dwordx4 v[236:237], off
	s_waitcnt vmcnt(8)
	s_waitcnt lgkmcnt(0)
	s_barrier
	s_waitcnt lgkmcnt(0)
	v_mfma_f32_16x16x32_bf16 v[124:127], v[144:147], v[200:203], v[124:127]
	v_mfma_f32_16x16x32_bf16 v[120:123], v[152:155], v[200:203], v[120:123]
	v_mfma_f32_16x16x32_bf16 v[108:111], v[144:147], v[208:211], v[108:111]
	v_mfma_f32_16x16x32_bf16 v[104:107], v[152:155], v[208:211], v[104:107]
	v_mfma_f32_16x16x32_bf16 v[92:95], v[144:147], v[216:219], v[92:95]
	v_mfma_f32_16x16x32_bf16 v[88:91], v[152:155], v[216:219], v[88:91]
	v_mfma_f32_16x16x32_bf16 v[76:79], v[144:147], v[224:227], v[76:79]
	v_mfma_f32_16x16x32_bf16 v[72:75], v[152:155], v[224:227], v[72:75]
	v_mfma_f32_16x16x32_bf16 v[124:127], v[148:151], v[204:207], v[124:127]
	v_mfma_f32_16x16x32_bf16 v[120:123], v[156:159], v[204:207], v[120:123]
	v_mfma_f32_16x16x32_bf16 v[108:111], v[148:151], v[212:215], v[108:111]
	v_mfma_f32_16x16x32_bf16 v[104:107], v[156:159], v[212:215], v[104:107]
	v_mfma_f32_16x16x32_bf16 v[92:95], v[148:151], v[220:223], v[92:95]
	v_mfma_f32_16x16x32_bf16 v[88:91], v[156:159], v[220:223], v[88:91]
	v_mfma_f32_16x16x32_bf16 v[76:79], v[148:151], v[228:231], v[76:79]
	v_mfma_f32_16x16x32_bf16 v[72:75], v[156:159], v[228:231], v[72:75]
	v_mfma_f32_16x16x32_bf16 v[116:119], v[184:187], v[200:203], v[116:119]
	v_mfma_f32_16x16x32_bf16 v[112:115], v[192:195], v[200:203], v[112:115]
	v_mfma_f32_16x16x32_bf16 v[100:103], v[184:187], v[208:211], v[100:103]
	v_mfma_f32_16x16x32_bf16 v[96:99], v[192:195], v[208:211], v[96:99]
	v_mfma_f32_16x16x32_bf16 v[84:87], v[184:187], v[216:219], v[84:87]
	v_mfma_f32_16x16x32_bf16 v[80:83], v[192:195], v[216:219], v[80:83]
	v_mfma_f32_16x16x32_bf16 v[68:71], v[184:187], v[224:227], v[68:71]
	v_mfma_f32_16x16x32_bf16 v[64:67], v[192:195], v[224:227], v[64:67]
	v_mfma_f32_16x16x32_bf16 v[116:119], v[188:191], v[204:207], v[116:119]
	v_mfma_f32_16x16x32_bf16 v[112:115], v[196:199], v[204:207], v[112:115]
	v_mfma_f32_16x16x32_bf16 v[100:103], v[188:191], v[212:215], v[100:103]
	v_mfma_f32_16x16x32_bf16 v[96:99], v[196:199], v[212:215], v[96:99]
	v_mfma_f32_16x16x32_bf16 v[84:87], v[188:191], v[220:223], v[84:87]
	v_mfma_f32_16x16x32_bf16 v[80:83], v[196:199], v[220:223], v[80:83]
	s_setprio 3
	s_barrier
	v_mfma_f32_16x16x32_bf16 v[68:71], v[188:191], v[228:231], v[68:71]
	v_mfma_f32_16x16x32_bf16 v[64:67], v[196:199], v[228:231], v[64:67]
	s_setprio 0
	s_add_i32 s34, s57, s37
	v_lshl_add_u64 v[160:161], v[160:161], 0, s[14:15]
	s_mov_b32 m0, s34
	ds_read_b128 v[200:203], v175 offset:49152
	ds_read_b128 v[204:207], v175 offset:50176
	ds_read_b128 v[208:211], v175 offset:51200
	ds_read_b128 v[212:215], v175 offset:52224
	ds_read_b128 v[216:219], v175 offset:53248
	ds_read_b128 v[220:223], v175 offset:54272
	ds_read_b128 v[224:227], v175 offset:55296
	ds_read_b128 v[228:231], v175 offset:56320
	global_load_lds_dwordx4 v[160:161], off
	s_add_i32 m0, s34, 0x2000
	s_add_u32 s30, s30, 0x40080
	v_lshl_add_u64 v[160:161], v[178:179], 0, s[14:15]
	s_addc_u32 s31, s31, 0
	s_add_i32 s34, s58, s37
	global_load_lds_dwordx4 v[160:161], off
	v_lshl_add_u64 v[160:161], s[30:31], 0, v[130:131]
	s_mov_b32 m0, s34
	s_nop 0
	global_load_lds_dwordx4 v[160:161], off
	v_lshl_add_u64 v[160:161], s[30:31], 0, v[134:135]
	s_add_i32 m0, s34, 0x2000
	s_nop 0
	global_load_lds_dwordx4 v[160:161], off
	s_waitcnt vmcnt(6)
	s_waitcnt lgkmcnt(0)
	s_barrier
	s_waitcnt lgkmcnt(0)
	v_mfma_f32_16x16x32_bf16 v[60:63], v[144:147], v[200:203], v[60:63]
	v_mfma_f32_16x16x32_bf16 v[56:59], v[152:155], v[200:203], v[56:59]
	v_mfma_f32_16x16x32_bf16 v[44:47], v[144:147], v[208:211], v[44:47]
	v_mfma_f32_16x16x32_bf16 v[40:43], v[152:155], v[208:211], v[40:43]
	v_mfma_f32_16x16x32_bf16 v[28:31], v[144:147], v[216:219], v[28:31]
	v_mfma_f32_16x16x32_bf16 v[24:27], v[152:155], v[216:219], v[24:27]
	v_mfma_f32_16x16x32_bf16 v[12:15], v[144:147], v[224:227], v[12:15]
	v_mfma_f32_16x16x32_bf16 v[8:11], v[152:155], v[224:227], v[8:11]
	v_mfma_f32_16x16x32_bf16 v[60:63], v[148:151], v[204:207], v[60:63]
	v_mfma_f32_16x16x32_bf16 v[56:59], v[156:159], v[204:207], v[56:59]
	v_mfma_f32_16x16x32_bf16 v[44:47], v[148:151], v[212:215], v[44:47]
	v_mfma_f32_16x16x32_bf16 v[40:43], v[156:159], v[212:215], v[40:43]
	v_mfma_f32_16x16x32_bf16 v[28:31], v[148:151], v[220:223], v[28:31]
	v_mfma_f32_16x16x32_bf16 v[24:27], v[156:159], v[220:223], v[24:27]
	v_mfma_f32_16x16x32_bf16 v[12:15], v[148:151], v[228:231], v[12:15]
	v_mfma_f32_16x16x32_bf16 v[8:11], v[156:159], v[228:231], v[8:11]
	v_mfma_f32_16x16x32_bf16 v[52:55], v[184:187], v[200:203], v[52:55]
	v_mfma_f32_16x16x32_bf16 v[48:51], v[192:195], v[200:203], v[48:51]
	v_mfma_f32_16x16x32_bf16 v[36:39], v[184:187], v[208:211], v[36:39]
	v_mfma_f32_16x16x32_bf16 v[32:35], v[192:195], v[208:211], v[32:35]
	v_mfma_f32_16x16x32_bf16 v[20:23], v[184:187], v[216:219], v[20:23]
	v_mfma_f32_16x16x32_bf16 v[16:19], v[192:195], v[216:219], v[16:19]
	v_mfma_f32_16x16x32_bf16 v[4:7], v[184:187], v[224:227], v[4:7]
	v_mfma_f32_16x16x32_bf16 v[0:3], v[192:195], v[224:227], v[0:3]
	v_mfma_f32_16x16x32_bf16 v[52:55], v[188:191], v[204:207], v[52:55]
	v_mfma_f32_16x16x32_bf16 v[48:51], v[196:199], v[204:207], v[48:51]
	v_mfma_f32_16x16x32_bf16 v[36:39], v[188:191], v[212:215], v[36:39]
	v_mfma_f32_16x16x32_bf16 v[32:35], v[196:199], v[212:215], v[32:35]
	v_mfma_f32_16x16x32_bf16 v[20:23], v[188:191], v[220:223], v[20:23]
	v_mfma_f32_16x16x32_bf16 v[16:19], v[196:199], v[220:223], v[16:19]
	s_setprio 3
	s_barrier
	v_mfma_f32_16x16x32_bf16 v[4:7], v[188:191], v[228:231], v[4:7]
	v_mfma_f32_16x16x32_bf16 v[0:3], v[196:199], v[228:231], v[0:3]
	s_setprio 0
	v_lshl_add_u64 v[160:161], v[232:233], 0, s[14:15]
	s_mov_b32 m0, s42
	s_nop 0
	global_load_lds_dwordx4 v[160:161], off
	v_lshl_add_u64 v[160:161], v[234:235], 0, s[14:15]
	s_mov_b32 m0, s43
	s_nop 0
	global_load_lds_dwordx4 v[160:161], off
	s_add_i32 s56, s56, 2
	s_add_u32 s28, s28, 0x100
	s_addc_u32 s29, s29, 0
	s_add_u32 s54, s54, 0x100
	s_addc_u32 s55, s55, 0
	s_cmp_gt_u32 s56, 13
	s_cbranch_scc0 .LBB0_877
	s_and_b64 vcc, exec, s[16:17]
	s_cbranch_vccz .LBB0_880
	s_barrier

.LBB0_1291:
	ds_read_b128 v[144:147], v151
	ds_read_b128 v[156:159], v151 offset:1024
	ds_read_b128 v[160:163], v151 offset:2048
	ds_read_b128 v[164:167], v151 offset:3072
	ds_read_b128 v[168:171], v152
	ds_read_b128 v[172:175], v152 offset:1024
	ds_read_b128 v[176:179], v152 offset:2048
	ds_read_b128 v[184:187], v152 offset:3072
	s_add_u32 s26, s24, 0xfffc0080
	s_addc_u32 s27, s25, -1
	s_cmp_eq_u32 s47, 12
	s_cselect_b32 s29, s17, s27
	s_cselect_b32 s28, s23, s26
	s_cselect_b32 s27, s15, s46
	s_cselect_b32 s26, s44, s45
	v_lshl_add_u64 v[220:221], s[24:25], 0, v[136:137]
	s_add_i32 m0, s34, 0xc000
	ds_read_b128 v[188:191], v153
	ds_read_b128 v[192:195], v153 offset:1024
	ds_read_b128 v[196:199], v153 offset:2048
	ds_read_b128 v[200:203], v153 offset:3072
	ds_read_b128 v[204:207], v153 offset:4096
	ds_read_b128 v[208:211], v153 offset:5120
	ds_read_b128 v[212:215], v153 offset:6144
	ds_read_b128 v[216:219], v153 offset:7168
	global_load_lds_dwordx4 v[220:221], off
	v_lshl_add_u64 v[220:221], s[24:25], 0, v[138:139]
	s_add_i32 m0, s34, 0xe000
	s_nop 0
	global_load_lds_dwordx4 v[220:221], off
	s_waitcnt vmcnt(8)
	s_waitcnt lgkmcnt(0)
	s_barrier
	s_waitcnt lgkmcnt(0)
	v_mfma_f32_16x16x32_bf16 v[124:127], v[144:147], v[188:191], v[124:127]
	v_mfma_f32_16x16x32_bf16 v[120:123], v[160:163], v[188:191], v[120:123]
	v_mfma_f32_16x16x32_bf16 v[108:111], v[144:147], v[196:199], v[108:111]
	v_mfma_f32_16x16x32_bf16 v[104:107], v[160:163], v[196:199], v[104:107]
	v_mfma_f32_16x16x32_bf16 v[92:95], v[144:147], v[204:207], v[92:95]
	v_mfma_f32_16x16x32_bf16 v[88:91], v[160:163], v[204:207], v[88:91]
	v_mfma_f32_16x16x32_bf16 v[76:79], v[144:147], v[212:215], v[76:79]
	v_mfma_f32_16x16x32_bf16 v[72:75], v[160:163], v[212:215], v[72:75]
	v_mfma_f32_16x16x32_bf16 v[124:127], v[156:159], v[192:195], v[124:127]
	v_mfma_f32_16x16x32_bf16 v[120:123], v[164:167], v[192:195], v[120:123]
	v_mfma_f32_16x16x32_bf16 v[108:111], v[156:159], v[200:203], v[108:111]
	v_mfma_f32_16x16x32_bf16 v[104:107], v[164:167], v[200:203], v[104:107]
	v_mfma_f32_16x16x32_bf16 v[92:95], v[156:159], v[208:211], v[92:95]
	v_mfma_f32_16x16x32_bf16 v[88:91], v[164:167], v[208:211], v[88:91]
	v_mfma_f32_16x16x32_bf16 v[76:79], v[156:159], v[216:219], v[76:79]
	v_mfma_f32_16x16x32_bf16 v[72:75], v[164:167], v[216:219], v[72:75]
	v_mfma_f32_16x16x32_bf16 v[116:119], v[168:171], v[188:191], v[116:119]
	v_mfma_f32_16x16x32_bf16 v[112:115], v[176:179], v[188:191], v[112:115]
	v_mfma_f32_16x16x32_bf16 v[100:103], v[168:171], v[196:199], v[100:103]
	v_mfma_f32_16x16x32_bf16 v[96:99], v[176:179], v[196:199], v[96:99]
	v_mfma_f32_16x16x32_bf16 v[84:87], v[168:171], v[204:207], v[84:87]
	v_mfma_f32_16x16x32_bf16 v[80:83], v[176:179], v[204:207], v[80:83]
	v_mfma_f32_16x16x32_bf16 v[68:71], v[168:171], v[212:215], v[68:71]
	v_mfma_f32_16x16x32_bf16 v[64:67], v[176:179], v[212:215], v[64:67]
	v_mfma_f32_16x16x32_bf16 v[116:119], v[172:175], v[192:195], v[116:119]
	v_mfma_f32_16x16x32_bf16 v[112:115], v[184:187], v[192:195], v[112:115]
	v_mfma_f32_16x16x32_bf16 v[100:103], v[172:175], v[200:203], v[100:103]
	v_mfma_f32_16x16x32_bf16 v[96:99], v[184:187], v[200:203], v[96:99]
	v_mfma_f32_16x16x32_bf16 v[84:87], v[172:175], v[208:211], v[84:87]
	v_mfma_f32_16x16x32_bf16 v[80:83], v[184:187], v[208:211], v[80:83]
	s_setprio 3
	s_barrier
	v_mfma_f32_16x16x32_bf16 v[68:71], v[172:175], v[216:219], v[68:71]
	v_mfma_f32_16x16x32_bf16 v[64:67], v[184:187], v[216:219], v[64:67]
	s_setprio 0
	s_add_i32 s50, s41, s33
	v_lshl_add_u64 v[220:221], s[26:27], 0, v[130:131]
	s_mov_b32 m0, s50
	ds_read_b128 v[188:191], v153 offset:16384
	ds_read_b128 v[192:195], v153 offset:17408
	ds_read_b128 v[196:199], v153 offset:18432
	ds_read_b128 v[200:203], v153 offset:19456
	ds_read_b128 v[204:207], v153 offset:20480
	ds_read_b128 v[208:211], v153 offset:21504
	ds_read_b128 v[212:215], v153 offset:22528
	ds_read_b128 v[216:219], v153 offset:23552
	global_load_lds_dwordx4 v[220:221], off
	s_add_i32 m0, s50, 0x2000
	s_add_u32 s50, s26, 0x40000
	v_lshl_add_u64 v[222:223], s[26:27], 0, v[134:135]
	s_addc_u32 s51, s27, 0
	s_add_i32 s52, s42, s33
	global_load_lds_dwordx4 v[222:223], off
	v_lshl_add_u64 v[224:225], s[50:51], 0, v[130:131]
	s_mov_b32 m0, s52
	global_load_lds_dwordx4 v[224:225], off
	v_lshl_add_u64 v[224:225], s[50:51], 0, v[134:135]
	s_add_i32 m0, s52, 0x2000
	s_nop 0
	global_load_lds_dwordx4 v[224:225], off
	s_waitcnt vmcnt(6)
	s_waitcnt lgkmcnt(0)
	s_barrier
	s_waitcnt lgkmcnt(0)
	v_mfma_f32_16x16x32_bf16 v[60:63], v[144:147], v[188:191], v[60:63]
	v_mfma_f32_16x16x32_bf16 v[56:59], v[160:163], v[188:191], v[56:59]
	v_mfma_f32_16x16x32_bf16 v[44:47], v[144:147], v[196:199], v[44:47]
	v_mfma_f32_16x16x32_bf16 v[40:43], v[160:163], v[196:199], v[40:43]
	v_mfma_f32_16x16x32_bf16 v[28:31], v[144:147], v[204:207], v[28:31]
	v_mfma_f32_16x16x32_bf16 v[24:27], v[160:163], v[204:207], v[24:27]
	v_mfma_f32_16x16x32_bf16 v[12:15], v[144:147], v[212:215], v[12:15]
	v_mfma_f32_16x16x32_bf16 v[8:11], v[160:163], v[212:215], v[8:11]
	v_mfma_f32_16x16x32_bf16 v[60:63], v[156:159], v[192:195], v[60:63]
	v_mfma_f32_16x16x32_bf16 v[56:59], v[164:167], v[192:195], v[56:59]
	v_mfma_f32_16x16x32_bf16 v[44:47], v[156:159], v[200:203], v[44:47]
	v_mfma_f32_16x16x32_bf16 v[40:43], v[164:167], v[200:203], v[40:43]
	v_mfma_f32_16x16x32_bf16 v[28:31], v[156:159], v[208:211], v[28:31]
	v_mfma_f32_16x16x32_bf16 v[24:27], v[164:167], v[208:211], v[24:27]
	v_mfma_f32_16x16x32_bf16 v[12:15], v[156:159], v[216:219], v[12:15]
	v_mfma_f32_16x16x32_bf16 v[8:11], v[164:167], v[216:219], v[8:11]
	v_mfma_f32_16x16x32_bf16 v[52:55], v[168:171], v[188:191], v[52:55]
	v_mfma_f32_16x16x32_bf16 v[48:51], v[176:179], v[188:191], v[48:51]
	v_mfma_f32_16x16x32_bf16 v[36:39], v[168:171], v[196:199], v[36:39]
	v_mfma_f32_16x16x32_bf16 v[32:35], v[176:179], v[196:199], v[32:35]
	v_mfma_f32_16x16x32_bf16 v[20:23], v[168:171], v[204:207], v[20:23]
	v_mfma_f32_16x16x32_bf16 v[16:19], v[176:179], v[204:207], v[16:19]
	v_mfma_f32_16x16x32_bf16 v[4:7], v[168:171], v[212:215], v[4:7]
	v_mfma_f32_16x16x32_bf16 v[0:3], v[176:179], v[212:215], v[0:3]
	v_mfma_f32_16x16x32_bf16 v[52:55], v[172:175], v[192:195], v[52:55]
	v_mfma_f32_16x16x32_bf16 v[48:51], v[184:187], v[192:195], v[48:51]
	v_mfma_f32_16x16x32_bf16 v[36:39], v[172:175], v[200:203], v[36:39]
	v_mfma_f32_16x16x32_bf16 v[32:35], v[184:187], v[200:203], v[32:35]
	v_mfma_f32_16x16x32_bf16 v[20:23], v[172:175], v[208:211], v[20:23]
	v_mfma_f32_16x16x32_bf16 v[16:19], v[184:187], v[208:211], v[16:19]
	s_setprio 3
	s_barrier
	v_mfma_f32_16x16x32_bf16 v[4:7], v[172:175], v[216:219], v[4:7]
	v_mfma_f32_16x16x32_bf16 v[0:3], v[184:187], v[216:219], v[0:3]
	s_setprio 0
	s_add_i32 s50, 0, 0x18000
	v_add_u32_e32 v155, s50, v149
	s_add_i32 s51, 0, 0x1c000
	ds_read_b128 v[144:147], v155
	ds_read_b128 v[156:159], v155 offset:1024
	ds_read_b128 v[160:163], v155 offset:2048
	ds_read_b128 v[164:167], v155 offset:3072
	v_add_u32_e32 v155, s51, v149
	ds_read_b128 v[168:171], v155
	ds_read_b128 v[172:175], v155 offset:1024
	ds_read_b128 v[176:179], v155 offset:2048
	ds_read_b128 v[184:187], v155 offset:3072
	v_lshl_add_u64 v[224:225], s[28:29], 0, v[128:129]
	s_mov_b32 m0, s34
	v_lshl_add_u64 v[226:227], s[28:29], 0, v[132:133]
	global_load_lds_dwordx4 v[224:225], off
	s_mov_b32 m0, s35
	s_nop 0
	global_load_lds_dwordx4 v[226:227], off
	s_add_u32 s28, s28, 0x40000
	s_addc_u32 s29, s29, 0
	s_mov_b32 m0, s36
	v_lshl_add_u64 v[228:229], s[28:29], 0, v[128:129]
	ds_read_b128 v[188:191], v153 offset:32768
	ds_read_b128 v[192:195], v153 offset:33792
	ds_read_b128 v[196:199], v153 offset:34816
	ds_read_b128 v[200:203], v153 offset:35840
	ds_read_b128 v[204:207], v153 offset:36864
	ds_read_b128 v[208:211], v153 offset:37888
	ds_read_b128 v[212:215], v153 offset:38912
	ds_read_b128 v[216:219], v153 offset:39936
	global_load_lds_dwordx4 v[228:229], off
	v_lshl_add_u64 v[228:229], s[28:29], 0, v[132:133]
	s_mov_b32 m0, s37
	s_nop 0
	global_load_lds_dwordx4 v[228:229], off
	s_waitcnt vmcnt(8)
	s_waitcnt lgkmcnt(0)
	s_barrier
	s_waitcnt lgkmcnt(0)
	v_mfma_f32_16x16x32_bf16 v[124:127], v[144:147], v[188:191], v[124:127]
	v_mfma_f32_16x16x32_bf16 v[120:123], v[160:163], v[188:191], v[120:123]
	v_mfma_f32_16x16x32_bf16 v[108:111], v[144:147], v[196:199], v[108:111]
	v_mfma_f32_16x16x32_bf16 v[104:107], v[160:163], v[196:199], v[104:107]
	v_mfma_f32_16x16x32_bf16 v[92:95], v[144:147], v[204:207], v[92:95]
	v_mfma_f32_16x16x32_bf16 v[88:91], v[160:163], v[204:207], v[88:91]
	v_mfma_f32_16x16x32_bf16 v[76:79], v[144:147], v[212:215], v[76:79]
	v_mfma_f32_16x16x32_bf16 v[72:75], v[160:163], v[212:215], v[72:75]
	v_mfma_f32_16x16x32_bf16 v[124:127], v[156:159], v[192:195], v[124:127]
	v_mfma_f32_16x16x32_bf16 v[120:123], v[164:167], v[192:195], v[120:123]
	v_mfma_f32_16x16x32_bf16 v[108:111], v[156:159], v[200:203], v[108:111]
	v_mfma_f32_16x16x32_bf16 v[104:107], v[164:167], v[200:203], v[104:107]
	v_mfma_f32_16x16x32_bf16 v[92:95], v[156:159], v[208:211], v[92:95]
	v_mfma_f32_16x16x32_bf16 v[88:91], v[164:167], v[208:211], v[88:91]
	v_mfma_f32_16x16x32_bf16 v[76:79], v[156:159], v[216:219], v[76:79]
	v_mfma_f32_16x16x32_bf16 v[72:75], v[164:167], v[216:219], v[72:75]
	v_mfma_f32_16x16x32_bf16 v[116:119], v[168:171], v[188:191], v[116:119]
	v_mfma_f32_16x16x32_bf16 v[112:115], v[176:179], v[188:191], v[112:115]
	v_mfma_f32_16x16x32_bf16 v[100:103], v[168:171], v[196:199], v[100:103]
	v_mfma_f32_16x16x32_bf16 v[96:99], v[176:179], v[196:199], v[96:99]
	v_mfma_f32_16x16x32_bf16 v[84:87], v[168:171], v[204:207], v[84:87]
	v_mfma_f32_16x16x32_bf16 v[80:83], v[176:179], v[204:207], v[80:83]
	v_mfma_f32_16x16x32_bf16 v[68:71], v[168:171], v[212:215], v[68:71]
	v_mfma_f32_16x16x32_bf16 v[64:67], v[176:179], v[212:215], v[64:67]
	v_mfma_f32_16x16x32_bf16 v[116:119], v[172:175], v[192:195], v[116:119]
	v_mfma_f32_16x16x32_bf16 v[112:115], v[184:187], v[192:195], v[112:115]
	v_mfma_f32_16x16x32_bf16 v[100:103], v[172:175], v[200:203], v[100:103]
	v_mfma_f32_16x16x32_bf16 v[96:99], v[184:187], v[200:203], v[96:99]
	v_mfma_f32_16x16x32_bf16 v[84:87], v[172:175], v[208:211], v[84:87]
	v_mfma_f32_16x16x32_bf16 v[80:83], v[184:187], v[208:211], v[80:83]
	s_setprio 3
	s_barrier
	v_mfma_f32_16x16x32_bf16 v[68:71], v[172:175], v[216:219], v[68:71]
	v_mfma_f32_16x16x32_bf16 v[64:67], v[184:187], v[216:219], v[64:67]
	s_setprio 0
	s_add_i32 s28, s50, s33
	v_lshl_add_u64 v[220:221], v[220:221], 0, s[10:11]
	s_mov_b32 m0, s28
	ds_read_b128 v[188:191], v153 offset:49152
	ds_read_b128 v[192:195], v153 offset:50176
	ds_read_b128 v[196:199], v153 offset:51200
	ds_read_b128 v[200:203], v153 offset:52224
	ds_read_b128 v[204:207], v153 offset:53248
	ds_read_b128 v[208:211], v153 offset:54272
	ds_read_b128 v[212:215], v153 offset:55296
	ds_read_b128 v[216:219], v153 offset:56320
	global_load_lds_dwordx4 v[220:221], off
	s_add_i32 m0, s28, 0x2000
	s_add_u32 s26, s26, 0x40080
	v_lshl_add_u64 v[220:221], v[222:223], 0, s[10:11]
	s_addc_u32 s27, s27, 0
	s_add_i32 s28, s51, s33
	global_load_lds_dwordx4 v[220:221], off
	v_lshl_add_u64 v[220:221], s[26:27], 0, v[130:131]
	s_mov_b32 m0, s28
	s_nop 0
	global_load_lds_dwordx4 v[220:221], off
	v_lshl_add_u64 v[220:221], s[26:27], 0, v[134:135]
	s_add_i32 m0, s28, 0x2000
	s_nop 0
	global_load_lds_dwordx4 v[220:221], off
	s_waitcnt vmcnt(6)
	s_waitcnt lgkmcnt(0)
	s_barrier
	s_waitcnt lgkmcnt(0)
	v_mfma_f32_16x16x32_bf16 v[60:63], v[144:147], v[188:191], v[60:63]
	v_mfma_f32_16x16x32_bf16 v[56:59], v[160:163], v[188:191], v[56:59]
	v_mfma_f32_16x16x32_bf16 v[44:47], v[144:147], v[196:199], v[44:47]
	v_mfma_f32_16x16x32_bf16 v[40:43], v[160:163], v[196:199], v[40:43]
	v_mfma_f32_16x16x32_bf16 v[28:31], v[144:147], v[204:207], v[28:31]
	v_mfma_f32_16x16x32_bf16 v[24:27], v[160:163], v[204:207], v[24:27]
	v_mfma_f32_16x16x32_bf16 v[12:15], v[144:147], v[212:215], v[12:15]
	v_mfma_f32_16x16x32_bf16 v[8:11], v[160:163], v[212:215], v[8:11]
	v_mfma_f32_16x16x32_bf16 v[60:63], v[156:159], v[192:195], v[60:63]
	v_mfma_f32_16x16x32_bf16 v[56:59], v[164:167], v[192:195], v[56:59]
	v_mfma_f32_16x16x32_bf16 v[44:47], v[156:159], v[200:203], v[44:47]
	v_mfma_f32_16x16x32_bf16 v[40:43], v[164:167], v[200:203], v[40:43]
	v_mfma_f32_16x16x32_bf16 v[28:31], v[156:159], v[208:211], v[28:31]
	v_mfma_f32_16x16x32_bf16 v[24:27], v[164:167], v[208:211], v[24:27]
	v_mfma_f32_16x16x32_bf16 v[12:15], v[156:159], v[216:219], v[12:15]
	v_mfma_f32_16x16x32_bf16 v[8:11], v[164:167], v[216:219], v[8:11]
	v_mfma_f32_16x16x32_bf16 v[52:55], v[168:171], v[188:191], v[52:55]
	v_mfma_f32_16x16x32_bf16 v[48:51], v[176:179], v[188:191], v[48:51]
	v_mfma_f32_16x16x32_bf16 v[36:39], v[168:171], v[196:199], v[36:39]
	v_mfma_f32_16x16x32_bf16 v[32:35], v[176:179], v[196:199], v[32:35]
	v_mfma_f32_16x16x32_bf16 v[20:23], v[168:171], v[204:207], v[20:23]
	v_mfma_f32_16x16x32_bf16 v[16:19], v[176:179], v[204:207], v[16:19]
	v_mfma_f32_16x16x32_bf16 v[4:7], v[168:171], v[212:215], v[4:7]
	v_mfma_f32_16x16x32_bf16 v[0:3], v[176:179], v[212:215], v[0:3]
	v_mfma_f32_16x16x32_bf16 v[52:55], v[172:175], v[192:195], v[52:55]
	v_mfma_f32_16x16x32_bf16 v[48:51], v[184:187], v[192:195], v[48:51]
	v_mfma_f32_16x16x32_bf16 v[36:39], v[172:175], v[200:203], v[36:39]
	v_mfma_f32_16x16x32_bf16 v[32:35], v[184:187], v[200:203], v[32:35]
	v_mfma_f32_16x16x32_bf16 v[20:23], v[172:175], v[208:211], v[20:23]
	v_mfma_f32_16x16x32_bf16 v[16:19], v[184:187], v[208:211], v[16:19]
	s_setprio 3
	s_barrier
	v_mfma_f32_16x16x32_bf16 v[4:7], v[172:175], v[216:219], v[4:7]
	v_mfma_f32_16x16x32_bf16 v[0:3], v[184:187], v[216:219], v[0:3]
	s_setprio 0
	v_lshl_add_u64 v[220:221], v[224:225], 0, s[10:11]
	s_mov_b32 m0, s39
	s_nop 0
	global_load_lds_dwordx4 v[220:221], off
	v_lshl_add_u64 v[220:221], v[226:227], 0, s[10:11]
	s_mov_b32 m0, s40
	s_nop 0
	global_load_lds_dwordx4 v[220:221], off
	s_add_i32 s47, s47, 2
	s_add_u32 s24, s24, 0x100
	s_addc_u32 s25, s25, 0
	s_add_u32 s45, s45, 0x100
	s_addc_u32 s46, s46, 0
	s_cmp_gt_u32 s47, 13
	s_cbranch_scc0 .LBB0_1291
	s_and_b64 vcc, exec, s[12:13]
	s_cbranch_vccz .LBB0_1294
	s_barrier

.LBB0_1379:
	ds_read_b128 v[154:157], v151
	ds_read_b128 v[158:161], v151 offset:1024
	ds_read_b128 v[162:165], v151 offset:2048
	ds_read_b128 v[166:169], v151 offset:3072
	ds_read_b128 v[170:173], v152
	ds_read_b128 v[174:177], v152 offset:1024
	ds_read_b128 v[184:187], v152 offset:2048
	ds_read_b128 v[188:191], v152 offset:3072
	s_add_u32 s22, s20, 0xfffc0080
	s_addc_u32 s23, s21, -1
	s_cmp_eq_u32 s46, 12
	s_cselect_b32 s25, s13, s23
	s_cselect_b32 s24, s42, s22
	s_cselect_b32 s23, s11, s45
	s_cselect_b32 s22, s43, s44
	v_lshl_add_u64 v[178:179], s[20:21], 0, v[136:137]
	s_add_i32 m0, s19, 0xc000
	ds_read_b128 v[192:195], v153
	ds_read_b128 v[196:199], v153 offset:1024
	ds_read_b128 v[200:203], v153 offset:2048
	ds_read_b128 v[204:207], v153 offset:3072
	ds_read_b128 v[208:211], v153 offset:4096
	ds_read_b128 v[212:215], v153 offset:5120
	ds_read_b128 v[216:219], v153 offset:6144
	ds_read_b128 v[220:223], v153 offset:7168
	global_load_lds_dwordx4 v[178:179], off
	v_lshl_add_u64 v[178:179], s[20:21], 0, v[138:139]
	s_add_i32 m0, s19, 0xe000
	s_nop 0
	global_load_lds_dwordx4 v[178:179], off
	s_waitcnt vmcnt(8)
	s_waitcnt lgkmcnt(0)
	s_barrier
	s_waitcnt lgkmcnt(0)
	v_mfma_f32_16x16x32_bf16 v[124:127], v[154:157], v[192:195], v[124:127]
	v_mfma_f32_16x16x32_bf16 v[116:119], v[162:165], v[192:195], v[116:119]
	v_mfma_f32_16x16x32_bf16 v[108:111], v[154:157], v[200:203], v[108:111]
	v_mfma_f32_16x16x32_bf16 v[100:103], v[162:165], v[200:203], v[100:103]
	v_mfma_f32_16x16x32_bf16 v[92:95], v[154:157], v[208:211], v[92:95]
	v_mfma_f32_16x16x32_bf16 v[84:87], v[162:165], v[208:211], v[84:87]
	v_mfma_f32_16x16x32_bf16 v[76:79], v[154:157], v[216:219], v[76:79]
	v_mfma_f32_16x16x32_bf16 v[68:71], v[162:165], v[216:219], v[68:71]
	v_mfma_f32_16x16x32_bf16 v[124:127], v[158:161], v[196:199], v[124:127]
	v_mfma_f32_16x16x32_bf16 v[116:119], v[166:169], v[196:199], v[116:119]
	v_mfma_f32_16x16x32_bf16 v[108:111], v[158:161], v[204:207], v[108:111]
	v_mfma_f32_16x16x32_bf16 v[100:103], v[166:169], v[204:207], v[100:103]
	v_mfma_f32_16x16x32_bf16 v[92:95], v[158:161], v[212:215], v[92:95]
	v_mfma_f32_16x16x32_bf16 v[84:87], v[166:169], v[212:215], v[84:87]
	v_mfma_f32_16x16x32_bf16 v[76:79], v[158:161], v[220:223], v[76:79]
	v_mfma_f32_16x16x32_bf16 v[68:71], v[166:169], v[220:223], v[68:71]
	v_mfma_f32_16x16x32_bf16 v[120:123], v[170:173], v[192:195], v[120:123]
	v_mfma_f32_16x16x32_bf16 v[112:115], v[184:187], v[192:195], v[112:115]
	v_mfma_f32_16x16x32_bf16 v[104:107], v[170:173], v[200:203], v[104:107]
	v_mfma_f32_16x16x32_bf16 v[96:99], v[184:187], v[200:203], v[96:99]
	v_mfma_f32_16x16x32_bf16 v[88:91], v[170:173], v[208:211], v[88:91]
	v_mfma_f32_16x16x32_bf16 v[80:83], v[184:187], v[208:211], v[80:83]
	v_mfma_f32_16x16x32_bf16 v[72:75], v[170:173], v[216:219], v[72:75]
	v_mfma_f32_16x16x32_bf16 v[64:67], v[184:187], v[216:219], v[64:67]
	v_mfma_f32_16x16x32_bf16 v[120:123], v[174:177], v[196:199], v[120:123]
	v_mfma_f32_16x16x32_bf16 v[112:115], v[188:191], v[196:199], v[112:115]
	v_mfma_f32_16x16x32_bf16 v[104:107], v[174:177], v[204:207], v[104:107]
	v_mfma_f32_16x16x32_bf16 v[96:99], v[188:191], v[204:207], v[96:99]
	v_mfma_f32_16x16x32_bf16 v[88:91], v[174:177], v[212:215], v[88:91]
	v_mfma_f32_16x16x32_bf16 v[80:83], v[188:191], v[212:215], v[80:83]
	s_setprio 3
	s_barrier
	v_mfma_f32_16x16x32_bf16 v[72:75], v[174:177], v[220:223], v[72:75]
	v_mfma_f32_16x16x32_bf16 v[64:67], v[188:191], v[220:223], v[64:67]
	s_setprio 0
	s_add_i32 s47, s36, s28
	v_lshl_add_u64 v[178:179], s[22:23], 0, v[132:133]
	s_mov_b32 m0, s47
	ds_read_b128 v[192:195], v153 offset:16384
	ds_read_b128 v[196:199], v153 offset:17408
	ds_read_b128 v[200:203], v153 offset:18432
	ds_read_b128 v[204:207], v153 offset:19456
	ds_read_b128 v[208:211], v153 offset:20480
	ds_read_b128 v[212:215], v153 offset:21504
	ds_read_b128 v[216:219], v153 offset:22528
	ds_read_b128 v[220:223], v153 offset:23552
	global_load_lds_dwordx4 v[178:179], off
	s_add_i32 m0, s47, 0x2000
	s_add_u32 s48, s22, 0x40000
	v_lshl_add_u64 v[224:225], s[22:23], 0, v[128:129]
	s_addc_u32 s49, s23, 0
	s_add_i32 s47, s37, s28
	global_load_lds_dwordx4 v[224:225], off
	v_lshl_add_u64 v[226:227], s[48:49], 0, v[132:133]
	s_mov_b32 m0, s47
	global_load_lds_dwordx4 v[226:227], off
	v_lshl_add_u64 v[226:227], s[48:49], 0, v[128:129]
	s_add_i32 m0, s47, 0x2000
	s_nop 0
	global_load_lds_dwordx4 v[226:227], off
	s_waitcnt vmcnt(6)
	s_waitcnt lgkmcnt(0)
	s_barrier
	s_waitcnt lgkmcnt(0)
	v_mfma_f32_16x16x32_bf16 v[60:63], v[154:157], v[192:195], v[60:63]
	v_mfma_f32_16x16x32_bf16 v[52:55], v[162:165], v[192:195], v[52:55]
	v_mfma_f32_16x16x32_bf16 v[44:47], v[154:157], v[200:203], v[44:47]
	v_mfma_f32_16x16x32_bf16 v[36:39], v[162:165], v[200:203], v[36:39]
	v_mfma_f32_16x16x32_bf16 v[28:31], v[154:157], v[208:211], v[28:31]
	v_mfma_f32_16x16x32_bf16 v[20:23], v[162:165], v[208:211], v[20:23]
	v_mfma_f32_16x16x32_bf16 v[12:15], v[154:157], v[216:219], v[12:15]
	v_mfma_f32_16x16x32_bf16 v[4:7], v[162:165], v[216:219], v[4:7]
	v_mfma_f32_16x16x32_bf16 v[60:63], v[158:161], v[196:199], v[60:63]
	v_mfma_f32_16x16x32_bf16 v[52:55], v[166:169], v[196:199], v[52:55]
	v_mfma_f32_16x16x32_bf16 v[44:47], v[158:161], v[204:207], v[44:47]
	v_mfma_f32_16x16x32_bf16 v[36:39], v[166:169], v[204:207], v[36:39]
	v_mfma_f32_16x16x32_bf16 v[28:31], v[158:161], v[212:215], v[28:31]
	v_mfma_f32_16x16x32_bf16 v[20:23], v[166:169], v[212:215], v[20:23]
	v_mfma_f32_16x16x32_bf16 v[12:15], v[158:161], v[220:223], v[12:15]
	v_mfma_f32_16x16x32_bf16 v[4:7], v[166:169], v[220:223], v[4:7]
	v_mfma_f32_16x16x32_bf16 v[56:59], v[170:173], v[192:195], v[56:59]
	v_mfma_f32_16x16x32_bf16 v[48:51], v[184:187], v[192:195], v[48:51]
	v_mfma_f32_16x16x32_bf16 v[40:43], v[170:173], v[200:203], v[40:43]
	v_mfma_f32_16x16x32_bf16 v[32:35], v[184:187], v[200:203], v[32:35]
	v_mfma_f32_16x16x32_bf16 v[24:27], v[170:173], v[208:211], v[24:27]
	v_mfma_f32_16x16x32_bf16 v[16:19], v[184:187], v[208:211], v[16:19]
	v_mfma_f32_16x16x32_bf16 v[8:11], v[170:173], v[216:219], v[8:11]
	v_mfma_f32_16x16x32_bf16 v[0:3], v[184:187], v[216:219], v[0:3]
	v_mfma_f32_16x16x32_bf16 v[56:59], v[174:177], v[196:199], v[56:59]
	v_mfma_f32_16x16x32_bf16 v[48:51], v[188:191], v[196:199], v[48:51]
	v_mfma_f32_16x16x32_bf16 v[40:43], v[174:177], v[204:207], v[40:43]
	v_mfma_f32_16x16x32_bf16 v[32:35], v[188:191], v[204:207], v[32:35]
	v_mfma_f32_16x16x32_bf16 v[24:27], v[174:177], v[212:215], v[24:27]
	v_mfma_f32_16x16x32_bf16 v[16:19], v[188:191], v[212:215], v[16:19]
	s_setprio 3
	s_barrier
	v_mfma_f32_16x16x32_bf16 v[8:11], v[174:177], v[220:223], v[8:11]
	v_mfma_f32_16x16x32_bf16 v[0:3], v[188:191], v[220:223], v[0:3]
	s_setprio 0
	s_add_i32 s47, 0, 0x18000
	s_add_i32 s48, 0, 0x1c000
	v_add_u32_e32 v166, s47, v145
	v_add_u32_e32 v180, s48, v145
	ds_read_b128 v[154:157], v166
	ds_read_b128 v[158:161], v166 offset:1024
	ds_read_b128 v[162:165], v166 offset:2048
	ds_read_b128 v[166:169], v166 offset:3072
	ds_read_b128 v[170:173], v180
	ds_read_b128 v[174:177], v180 offset:1024
	ds_read_b128 v[184:187], v180 offset:2048
	ds_read_b128 v[188:191], v180 offset:3072
	v_lshl_add_u64 v[226:227], s[24:25], 0, v[134:135]
	s_mov_b32 m0, s19
	v_lshl_add_u64 v[228:229], s[24:25], 0, v[130:131]
	global_load_lds_dwordx4 v[226:227], off
	s_mov_b32 m0, s30
	s_nop 0
	global_load_lds_dwordx4 v[228:229], off
	s_add_u32 s24, s24, 0x40000
	s_addc_u32 s25, s25, 0
	s_mov_b32 m0, s31
	v_lshl_add_u64 v[230:231], s[24:25], 0, v[134:135]
	ds_read_b128 v[192:195], v153 offset:32768
	ds_read_b128 v[196:199], v153 offset:33792
	ds_read_b128 v[200:203], v153 offset:34816
	ds_read_b128 v[204:207], v153 offset:35840
	ds_read_b128 v[208:211], v153 offset:36864
	ds_read_b128 v[212:215], v153 offset:37888
	ds_read_b128 v[216:219], v153 offset:38912
	ds_read_b128 v[220:223], v153 offset:39936
	global_load_lds_dwordx4 v[230:231], off
	v_lshl_add_u64 v[230:231], s[24:25], 0, v[130:131]
	s_mov_b32 m0, s33
	s_nop 0
	global_load_lds_dwordx4 v[230:231], off
	s_waitcnt vmcnt(8)
	s_waitcnt lgkmcnt(0)
	s_barrier
	s_waitcnt lgkmcnt(0)
	v_mfma_f32_16x16x32_bf16 v[124:127], v[154:157], v[192:195], v[124:127]
	v_mfma_f32_16x16x32_bf16 v[116:119], v[162:165], v[192:195], v[116:119]
	v_mfma_f32_16x16x32_bf16 v[108:111], v[154:157], v[200:203], v[108:111]
	v_mfma_f32_16x16x32_bf16 v[100:103], v[162:165], v[200:203], v[100:103]
	v_mfma_f32_16x16x32_bf16 v[92:95], v[154:157], v[208:211], v[92:95]
	v_mfma_f32_16x16x32_bf16 v[84:87], v[162:165], v[208:211], v[84:87]
	v_mfma_f32_16x16x32_bf16 v[76:79], v[154:157], v[216:219], v[76:79]
	v_mfma_f32_16x16x32_bf16 v[68:71], v[162:165], v[216:219], v[68:71]
	v_mfma_f32_16x16x32_bf16 v[124:127], v[158:161], v[196:199], v[124:127]
	v_mfma_f32_16x16x32_bf16 v[116:119], v[166:169], v[196:199], v[116:119]
	v_mfma_f32_16x16x32_bf16 v[108:111], v[158:161], v[204:207], v[108:111]
	v_mfma_f32_16x16x32_bf16 v[100:103], v[166:169], v[204:207], v[100:103]
	v_mfma_f32_16x16x32_bf16 v[92:95], v[158:161], v[212:215], v[92:95]
	v_mfma_f32_16x16x32_bf16 v[84:87], v[166:169], v[212:215], v[84:87]
	v_mfma_f32_16x16x32_bf16 v[76:79], v[158:161], v[220:223], v[76:79]
	v_mfma_f32_16x16x32_bf16 v[68:71], v[166:169], v[220:223], v[68:71]
	v_mfma_f32_16x16x32_bf16 v[120:123], v[170:173], v[192:195], v[120:123]
	v_mfma_f32_16x16x32_bf16 v[112:115], v[184:187], v[192:195], v[112:115]
	v_mfma_f32_16x16x32_bf16 v[104:107], v[170:173], v[200:203], v[104:107]
	v_mfma_f32_16x16x32_bf16 v[96:99], v[184:187], v[200:203], v[96:99]
	v_mfma_f32_16x16x32_bf16 v[88:91], v[170:173], v[208:211], v[88:91]
	v_mfma_f32_16x16x32_bf16 v[80:83], v[184:187], v[208:211], v[80:83]
	v_mfma_f32_16x16x32_bf16 v[72:75], v[170:173], v[216:219], v[72:75]
	v_mfma_f32_16x16x32_bf16 v[64:67], v[184:187], v[216:219], v[64:67]
	v_mfma_f32_16x16x32_bf16 v[120:123], v[174:177], v[196:199], v[120:123]
	v_mfma_f32_16x16x32_bf16 v[112:115], v[188:191], v[196:199], v[112:115]
	v_mfma_f32_16x16x32_bf16 v[104:107], v[174:177], v[204:207], v[104:107]
	v_mfma_f32_16x16x32_bf16 v[96:99], v[188:191], v[204:207], v[96:99]
	v_mfma_f32_16x16x32_bf16 v[88:91], v[174:177], v[212:215], v[88:91]
	v_mfma_f32_16x16x32_bf16 v[80:83], v[188:191], v[212:215], v[80:83]
	s_setprio 3
	s_barrier
	v_mfma_f32_16x16x32_bf16 v[72:75], v[174:177], v[220:223], v[72:75]
	v_mfma_f32_16x16x32_bf16 v[64:67], v[188:191], v[220:223], v[64:67]
	s_setprio 0
	s_add_i32 s24, s47, s28
	v_lshl_add_u64 v[178:179], v[178:179], 0, s[6:7]
	s_mov_b32 m0, s24
	ds_read_b128 v[192:195], v153 offset:49152
	ds_read_b128 v[196:199], v153 offset:50176
	ds_read_b128 v[200:203], v153 offset:51200
	ds_read_b128 v[204:207], v153 offset:52224
	ds_read_b128 v[208:211], v153 offset:53248
	ds_read_b128 v[212:215], v153 offset:54272
	ds_read_b128 v[216:219], v153 offset:55296
	ds_read_b128 v[220:223], v153 offset:56320
	global_load_lds_dwordx4 v[178:179], off
	s_add_i32 m0, s24, 0x2000
	s_add_u32 s22, s22, 0x40080
	v_lshl_add_u64 v[178:179], v[224:225], 0, s[6:7]
	s_addc_u32 s23, s23, 0
	s_add_i32 s24, s48, s28
	global_load_lds_dwordx4 v[178:179], off
	v_lshl_add_u64 v[178:179], s[22:23], 0, v[132:133]
	s_mov_b32 m0, s24
	s_nop 0
	global_load_lds_dwordx4 v[178:179], off
	v_lshl_add_u64 v[178:179], s[22:23], 0, v[128:129]
	s_add_i32 m0, s24, 0x2000
	s_nop 0
	global_load_lds_dwordx4 v[178:179], off
	s_waitcnt vmcnt(6)
	s_waitcnt lgkmcnt(0)
	s_barrier
	s_waitcnt lgkmcnt(0)
	v_mfma_f32_16x16x32_bf16 v[60:63], v[154:157], v[192:195], v[60:63]
	v_mfma_f32_16x16x32_bf16 v[52:55], v[162:165], v[192:195], v[52:55]
	v_mfma_f32_16x16x32_bf16 v[44:47], v[154:157], v[200:203], v[44:47]
	v_mfma_f32_16x16x32_bf16 v[36:39], v[162:165], v[200:203], v[36:39]
	v_mfma_f32_16x16x32_bf16 v[28:31], v[154:157], v[208:211], v[28:31]
	v_mfma_f32_16x16x32_bf16 v[20:23], v[162:165], v[208:211], v[20:23]
	v_mfma_f32_16x16x32_bf16 v[12:15], v[154:157], v[216:219], v[12:15]
	v_mfma_f32_16x16x32_bf16 v[4:7], v[162:165], v[216:219], v[4:7]
	v_mfma_f32_16x16x32_bf16 v[60:63], v[158:161], v[196:199], v[60:63]
	v_mfma_f32_16x16x32_bf16 v[52:55], v[166:169], v[196:199], v[52:55]
	v_mfma_f32_16x16x32_bf16 v[44:47], v[158:161], v[204:207], v[44:47]
	v_mfma_f32_16x16x32_bf16 v[36:39], v[166:169], v[204:207], v[36:39]
	v_mfma_f32_16x16x32_bf16 v[28:31], v[158:161], v[212:215], v[28:31]
	v_mfma_f32_16x16x32_bf16 v[20:23], v[166:169], v[212:215], v[20:23]
	v_mfma_f32_16x16x32_bf16 v[12:15], v[158:161], v[220:223], v[12:15]
	v_mfma_f32_16x16x32_bf16 v[4:7], v[166:169], v[220:223], v[4:7]
	v_mfma_f32_16x16x32_bf16 v[56:59], v[170:173], v[192:195], v[56:59]
	v_mfma_f32_16x16x32_bf16 v[48:51], v[184:187], v[192:195], v[48:51]
	v_mfma_f32_16x16x32_bf16 v[40:43], v[170:173], v[200:203], v[40:43]
	v_mfma_f32_16x16x32_bf16 v[32:35], v[184:187], v[200:203], v[32:35]
	v_mfma_f32_16x16x32_bf16 v[24:27], v[170:173], v[208:211], v[24:27]
	v_mfma_f32_16x16x32_bf16 v[16:19], v[184:187], v[208:211], v[16:19]
	v_mfma_f32_16x16x32_bf16 v[8:11], v[170:173], v[216:219], v[8:11]
	v_mfma_f32_16x16x32_bf16 v[0:3], v[184:187], v[216:219], v[0:3]
	v_mfma_f32_16x16x32_bf16 v[56:59], v[174:177], v[196:199], v[56:59]
	v_mfma_f32_16x16x32_bf16 v[48:51], v[188:191], v[196:199], v[48:51]
	v_mfma_f32_16x16x32_bf16 v[40:43], v[174:177], v[204:207], v[40:43]
	v_mfma_f32_16x16x32_bf16 v[32:35], v[188:191], v[204:207], v[32:35]
	v_mfma_f32_16x16x32_bf16 v[24:27], v[174:177], v[212:215], v[24:27]
	v_mfma_f32_16x16x32_bf16 v[16:19], v[188:191], v[212:215], v[16:19]
	s_setprio 3
	s_barrier
	v_mfma_f32_16x16x32_bf16 v[8:11], v[174:177], v[220:223], v[8:11]
	v_mfma_f32_16x16x32_bf16 v[0:3], v[188:191], v[220:223], v[0:3]
	s_setprio 0
	v_lshl_add_u64 v[178:179], v[226:227], 0, s[6:7]
	s_mov_b32 m0, s34
	s_nop 0
	global_load_lds_dwordx4 v[178:179], off
	v_lshl_add_u64 v[178:179], v[228:229], 0, s[6:7]
	s_mov_b32 m0, s35
	s_nop 0
	global_load_lds_dwordx4 v[178:179], off
	s_add_i32 s46, s46, 2
	s_add_u32 s20, s20, 0x100
	s_addc_u32 s21, s21, 0
	s_add_u32 s44, s44, 0x100
	s_addc_u32 s45, s45, 0
	s_cmp_gt_u32 s46, 13
	s_cbranch_scc0 .LBB0_1379
	s_and_b64 vcc, exec, s[8:9]
	s_cbranch_vccz .LBB0_1382
	s_barrier

.LBB0_1461:
	ds_read_b128 v[144:147], v151
	ds_read_b128 v[156:159], v151 offset:1024
	ds_read_b128 v[160:163], v151 offset:2048
	ds_read_b128 v[164:167], v151 offset:3072
	ds_read_b128 v[168:171], v152
	ds_read_b128 v[172:175], v152 offset:1024
	ds_read_b128 v[176:179], v152 offset:2048
	ds_read_b128 v[182:185], v152 offset:3072
	s_add_u32 s20, s18, 0x100
	s_addc_u32 s21, s19, 0
	s_cmp_eq_u32 s45, 40
	s_cselect_b32 s25, s7, s21
	s_cselect_b32 s24, s6, s20
	s_cselect_b32 s23, s17, s44
	s_cselect_b32 s22, s16, s43
	v_lshl_add_u64 v[218:219], s[18:19], 0, v[136:137]
	s_add_i32 m0, s29, 0xc000
	ds_read_b128 v[186:189], v153
	ds_read_b128 v[190:193], v153 offset:1024
	ds_read_b128 v[194:197], v153 offset:2048
	ds_read_b128 v[198:201], v153 offset:3072
	ds_read_b128 v[202:205], v153 offset:4096
	ds_read_b128 v[206:209], v153 offset:5120
	ds_read_b128 v[210:213], v153 offset:6144
	ds_read_b128 v[214:217], v153 offset:7168
	global_load_lds_dwordx4 v[218:219], off
	v_lshl_add_u64 v[218:219], s[18:19], 0, v[138:139]
	s_add_i32 m0, s29, 0xe000
	s_nop 0
	global_load_lds_dwordx4 v[218:219], off
	s_waitcnt vmcnt(8)
	s_waitcnt lgkmcnt(0)
	s_barrier
	s_waitcnt lgkmcnt(0)
	v_mfma_f32_16x16x32_bf16 v[124:127], v[144:147], v[186:189], v[124:127]
	v_mfma_f32_16x16x32_bf16 v[120:123], v[160:163], v[186:189], v[120:123]
	v_mfma_f32_16x16x32_bf16 v[108:111], v[144:147], v[194:197], v[108:111]
	v_mfma_f32_16x16x32_bf16 v[104:107], v[160:163], v[194:197], v[104:107]
	v_mfma_f32_16x16x32_bf16 v[92:95], v[144:147], v[202:205], v[92:95]
	v_mfma_f32_16x16x32_bf16 v[88:91], v[160:163], v[202:205], v[88:91]
	v_mfma_f32_16x16x32_bf16 v[76:79], v[144:147], v[210:213], v[76:79]
	v_mfma_f32_16x16x32_bf16 v[72:75], v[160:163], v[210:213], v[72:75]
	v_mfma_f32_16x16x32_bf16 v[124:127], v[156:159], v[190:193], v[124:127]
	v_mfma_f32_16x16x32_bf16 v[120:123], v[164:167], v[190:193], v[120:123]
	v_mfma_f32_16x16x32_bf16 v[108:111], v[156:159], v[198:201], v[108:111]
	v_mfma_f32_16x16x32_bf16 v[104:107], v[164:167], v[198:201], v[104:107]
	v_mfma_f32_16x16x32_bf16 v[92:95], v[156:159], v[206:209], v[92:95]
	v_mfma_f32_16x16x32_bf16 v[88:91], v[164:167], v[206:209], v[88:91]
	v_mfma_f32_16x16x32_bf16 v[76:79], v[156:159], v[214:217], v[76:79]
	v_mfma_f32_16x16x32_bf16 v[72:75], v[164:167], v[214:217], v[72:75]
	v_mfma_f32_16x16x32_bf16 v[116:119], v[168:171], v[186:189], v[116:119]
	v_mfma_f32_16x16x32_bf16 v[112:115], v[176:179], v[186:189], v[112:115]
	v_mfma_f32_16x16x32_bf16 v[100:103], v[168:171], v[194:197], v[100:103]
	v_mfma_f32_16x16x32_bf16 v[96:99], v[176:179], v[194:197], v[96:99]
	v_mfma_f32_16x16x32_bf16 v[84:87], v[168:171], v[202:205], v[84:87]
	v_mfma_f32_16x16x32_bf16 v[80:83], v[176:179], v[202:205], v[80:83]
	v_mfma_f32_16x16x32_bf16 v[68:71], v[168:171], v[210:213], v[68:71]
	v_mfma_f32_16x16x32_bf16 v[64:67], v[176:179], v[210:213], v[64:67]
	v_mfma_f32_16x16x32_bf16 v[116:119], v[172:175], v[190:193], v[116:119]
	v_mfma_f32_16x16x32_bf16 v[112:115], v[182:185], v[190:193], v[112:115]
	v_mfma_f32_16x16x32_bf16 v[100:103], v[172:175], v[198:201], v[100:103]
	v_mfma_f32_16x16x32_bf16 v[96:99], v[182:185], v[198:201], v[96:99]
	v_mfma_f32_16x16x32_bf16 v[84:87], v[172:175], v[206:209], v[84:87]
	v_mfma_f32_16x16x32_bf16 v[80:83], v[182:185], v[206:209], v[80:83]
	s_setprio 3
	s_barrier
	v_mfma_f32_16x16x32_bf16 v[68:71], v[172:175], v[214:217], v[68:71]
	v_mfma_f32_16x16x32_bf16 v[64:67], v[182:185], v[214:217], v[64:67]
	s_setprio 0
	s_add_i32 s18, s37, s28
	v_lshl_add_u64 v[218:219], s[22:23], 0, v[130:131]
	s_mov_b32 m0, s18
	ds_read_b128 v[186:189], v153 offset:16384
	ds_read_b128 v[190:193], v153 offset:17408
	ds_read_b128 v[194:197], v153 offset:18432
	ds_read_b128 v[198:201], v153 offset:19456
	ds_read_b128 v[202:205], v153 offset:20480
	ds_read_b128 v[206:209], v153 offset:21504
	ds_read_b128 v[210:213], v153 offset:22528
	ds_read_b128 v[214:217], v153 offset:23552
	global_load_lds_dwordx4 v[218:219], off
	s_add_i32 m0, s18, 0x2000
	s_add_u32 s18, s22, 0xb0000
	v_lshl_add_u64 v[220:221], s[22:23], 0, v[134:135]
	s_addc_u32 s19, s23, 0
	s_add_i32 s46, s38, s28
	global_load_lds_dwordx4 v[220:221], off
	v_lshl_add_u64 v[222:223], s[18:19], 0, v[130:131]
	s_mov_b32 m0, s46
	global_load_lds_dwordx4 v[222:223], off
	v_lshl_add_u64 v[222:223], s[18:19], 0, v[134:135]
	s_add_i32 m0, s46, 0x2000
	s_nop 0
	global_load_lds_dwordx4 v[222:223], off
	s_waitcnt vmcnt(6)
	s_waitcnt lgkmcnt(0)
	s_barrier
	s_waitcnt lgkmcnt(0)
	v_mfma_f32_16x16x32_bf16 v[60:63], v[144:147], v[186:189], v[60:63]
	v_mfma_f32_16x16x32_bf16 v[56:59], v[160:163], v[186:189], v[56:59]
	v_mfma_f32_16x16x32_bf16 v[44:47], v[144:147], v[194:197], v[44:47]
	v_mfma_f32_16x16x32_bf16 v[40:43], v[160:163], v[194:197], v[40:43]
	v_mfma_f32_16x16x32_bf16 v[28:31], v[144:147], v[202:205], v[28:31]
	v_mfma_f32_16x16x32_bf16 v[24:27], v[160:163], v[202:205], v[24:27]
	v_mfma_f32_16x16x32_bf16 v[12:15], v[144:147], v[210:213], v[12:15]
	v_mfma_f32_16x16x32_bf16 v[8:11], v[160:163], v[210:213], v[8:11]
	v_mfma_f32_16x16x32_bf16 v[60:63], v[156:159], v[190:193], v[60:63]
	v_mfma_f32_16x16x32_bf16 v[56:59], v[164:167], v[190:193], v[56:59]
	v_mfma_f32_16x16x32_bf16 v[44:47], v[156:159], v[198:201], v[44:47]
	v_mfma_f32_16x16x32_bf16 v[40:43], v[164:167], v[198:201], v[40:43]
	v_mfma_f32_16x16x32_bf16 v[28:31], v[156:159], v[206:209], v[28:31]
	v_mfma_f32_16x16x32_bf16 v[24:27], v[164:167], v[206:209], v[24:27]
	v_mfma_f32_16x16x32_bf16 v[12:15], v[156:159], v[214:217], v[12:15]
	v_mfma_f32_16x16x32_bf16 v[8:11], v[164:167], v[214:217], v[8:11]
	v_mfma_f32_16x16x32_bf16 v[52:55], v[168:171], v[186:189], v[52:55]
	v_mfma_f32_16x16x32_bf16 v[48:51], v[176:179], v[186:189], v[48:51]
	v_mfma_f32_16x16x32_bf16 v[36:39], v[168:171], v[194:197], v[36:39]
	v_mfma_f32_16x16x32_bf16 v[32:35], v[176:179], v[194:197], v[32:35]
	v_mfma_f32_16x16x32_bf16 v[20:23], v[168:171], v[202:205], v[20:23]
	v_mfma_f32_16x16x32_bf16 v[16:19], v[176:179], v[202:205], v[16:19]
	v_mfma_f32_16x16x32_bf16 v[4:7], v[168:171], v[210:213], v[4:7]
	v_mfma_f32_16x16x32_bf16 v[0:3], v[176:179], v[210:213], v[0:3]
	v_mfma_f32_16x16x32_bf16 v[52:55], v[172:175], v[190:193], v[52:55]
	v_mfma_f32_16x16x32_bf16 v[48:51], v[182:185], v[190:193], v[48:51]
	v_mfma_f32_16x16x32_bf16 v[36:39], v[172:175], v[198:201], v[36:39]
	v_mfma_f32_16x16x32_bf16 v[32:35], v[182:185], v[198:201], v[32:35]
	v_mfma_f32_16x16x32_bf16 v[20:23], v[172:175], v[206:209], v[20:23]
	v_mfma_f32_16x16x32_bf16 v[16:19], v[182:185], v[206:209], v[16:19]
	s_setprio 3
	s_barrier
	v_mfma_f32_16x16x32_bf16 v[4:7], v[172:175], v[214:217], v[4:7]
	v_mfma_f32_16x16x32_bf16 v[0:3], v[182:185], v[214:217], v[0:3]
	s_setprio 0
	s_add_i32 s46, 0, 0x18000
	v_add_u32_e32 v155, s46, v149
	s_add_i32 s47, 0, 0x1c000
	ds_read_b128 v[144:147], v155
	ds_read_b128 v[156:159], v155 offset:1024
	ds_read_b128 v[160:163], v155 offset:2048
	ds_read_b128 v[164:167], v155 offset:3072
	v_add_u32_e32 v155, s47, v149
	ds_read_b128 v[168:171], v155
	ds_read_b128 v[172:175], v155 offset:1024
	ds_read_b128 v[176:179], v155 offset:2048
	ds_read_b128 v[182:185], v155 offset:3072
	s_add_u32 s18, s24, 0xb0000
	s_addc_u32 s19, s25, 0
	v_lshl_add_u64 v[222:223], s[24:25], 0, v[128:129]
	s_mov_b32 m0, s29
	v_lshl_add_u64 v[224:225], s[24:25], 0, v[132:133]
	global_load_lds_dwordx4 v[222:223], off
	s_mov_b32 m0, s30
	s_nop 0
	global_load_lds_dwordx4 v[224:225], off
	s_mov_b32 m0, s31
	v_lshl_add_u64 v[226:227], s[18:19], 0, v[128:129]
	ds_read_b128 v[186:189], v153 offset:32768
	ds_read_b128 v[190:193], v153 offset:33792
	ds_read_b128 v[194:197], v153 offset:34816
	ds_read_b128 v[198:201], v153 offset:35840
	ds_read_b128 v[202:205], v153 offset:36864
	ds_read_b128 v[206:209], v153 offset:37888
	ds_read_b128 v[210:213], v153 offset:38912
	ds_read_b128 v[214:217], v153 offset:39936
	global_load_lds_dwordx4 v[226:227], off
	v_lshl_add_u64 v[226:227], s[18:19], 0, v[132:133]
	s_mov_b32 m0, s33
	s_nop 0
	global_load_lds_dwordx4 v[226:227], off
	s_waitcnt vmcnt(8)
	s_waitcnt lgkmcnt(0)
	s_barrier
	s_waitcnt lgkmcnt(0)
	v_mfma_f32_16x16x32_bf16 v[124:127], v[144:147], v[186:189], v[124:127]
	v_mfma_f32_16x16x32_bf16 v[120:123], v[160:163], v[186:189], v[120:123]
	v_mfma_f32_16x16x32_bf16 v[108:111], v[144:147], v[194:197], v[108:111]
	v_mfma_f32_16x16x32_bf16 v[104:107], v[160:163], v[194:197], v[104:107]
	v_mfma_f32_16x16x32_bf16 v[92:95], v[144:147], v[202:205], v[92:95]
	v_mfma_f32_16x16x32_bf16 v[88:91], v[160:163], v[202:205], v[88:91]
	v_mfma_f32_16x16x32_bf16 v[76:79], v[144:147], v[210:213], v[76:79]
	v_mfma_f32_16x16x32_bf16 v[72:75], v[160:163], v[210:213], v[72:75]
	v_mfma_f32_16x16x32_bf16 v[124:127], v[156:159], v[190:193], v[124:127]
	v_mfma_f32_16x16x32_bf16 v[120:123], v[164:167], v[190:193], v[120:123]
	v_mfma_f32_16x16x32_bf16 v[108:111], v[156:159], v[198:201], v[108:111]
	v_mfma_f32_16x16x32_bf16 v[104:107], v[164:167], v[198:201], v[104:107]
	v_mfma_f32_16x16x32_bf16 v[92:95], v[156:159], v[206:209], v[92:95]
	v_mfma_f32_16x16x32_bf16 v[88:91], v[164:167], v[206:209], v[88:91]
	v_mfma_f32_16x16x32_bf16 v[76:79], v[156:159], v[214:217], v[76:79]
	v_mfma_f32_16x16x32_bf16 v[72:75], v[164:167], v[214:217], v[72:75]
	v_mfma_f32_16x16x32_bf16 v[116:119], v[168:171], v[186:189], v[116:119]
	v_mfma_f32_16x16x32_bf16 v[112:115], v[176:179], v[186:189], v[112:115]
	v_mfma_f32_16x16x32_bf16 v[100:103], v[168:171], v[194:197], v[100:103]
	v_mfma_f32_16x16x32_bf16 v[96:99], v[176:179], v[194:197], v[96:99]
	v_mfma_f32_16x16x32_bf16 v[84:87], v[168:171], v[202:205], v[84:87]
	v_mfma_f32_16x16x32_bf16 v[80:83], v[176:179], v[202:205], v[80:83]
	v_mfma_f32_16x16x32_bf16 v[68:71], v[168:171], v[210:213], v[68:71]
	v_mfma_f32_16x16x32_bf16 v[64:67], v[176:179], v[210:213], v[64:67]
	v_mfma_f32_16x16x32_bf16 v[116:119], v[172:175], v[190:193], v[116:119]
	v_mfma_f32_16x16x32_bf16 v[112:115], v[182:185], v[190:193], v[112:115]
	v_mfma_f32_16x16x32_bf16 v[100:103], v[172:175], v[198:201], v[100:103]
	v_mfma_f32_16x16x32_bf16 v[96:99], v[182:185], v[198:201], v[96:99]
	v_mfma_f32_16x16x32_bf16 v[84:87], v[172:175], v[206:209], v[84:87]
	v_mfma_f32_16x16x32_bf16 v[80:83], v[182:185], v[206:209], v[80:83]
	s_setprio 3
	s_barrier
	v_mfma_f32_16x16x32_bf16 v[68:71], v[172:175], v[214:217], v[68:71]
	v_mfma_f32_16x16x32_bf16 v[64:67], v[182:185], v[214:217], v[64:67]
	s_setprio 0
	s_add_i32 s18, s46, s28
	v_lshl_add_u64 v[218:219], v[218:219], 0, s[12:13]
	s_mov_b32 m0, s18
	ds_read_b128 v[186:189], v153 offset:49152
	ds_read_b128 v[190:193], v153 offset:50176
	ds_read_b128 v[194:197], v153 offset:51200
	ds_read_b128 v[198:201], v153 offset:52224
	ds_read_b128 v[202:205], v153 offset:53248
	ds_read_b128 v[206:209], v153 offset:54272
	ds_read_b128 v[210:213], v153 offset:55296
	ds_read_b128 v[214:217], v153 offset:56320
	global_load_lds_dwordx4 v[218:219], off
	s_add_i32 m0, s18, 0x2000
	s_add_u32 s18, s22, 0xb0080
	v_lshl_add_u64 v[218:219], v[220:221], 0, s[12:13]
	s_addc_u32 s19, s23, 0
	s_add_i32 s22, s47, s28
	global_load_lds_dwordx4 v[218:219], off
	v_lshl_add_u64 v[218:219], s[18:19], 0, v[130:131]
	s_mov_b32 m0, s22
	s_nop 0
	global_load_lds_dwordx4 v[218:219], off
	v_lshl_add_u64 v[218:219], s[18:19], 0, v[134:135]
	s_add_i32 m0, s22, 0x2000
	s_nop 0
	global_load_lds_dwordx4 v[218:219], off
	s_waitcnt vmcnt(6)
	s_waitcnt lgkmcnt(0)
	s_barrier
	s_waitcnt lgkmcnt(0)
	v_mfma_f32_16x16x32_bf16 v[60:63], v[144:147], v[186:189], v[60:63]
	v_mfma_f32_16x16x32_bf16 v[56:59], v[160:163], v[186:189], v[56:59]
	v_mfma_f32_16x16x32_bf16 v[44:47], v[144:147], v[194:197], v[44:47]
	v_mfma_f32_16x16x32_bf16 v[40:43], v[160:163], v[194:197], v[40:43]
	v_mfma_f32_16x16x32_bf16 v[28:31], v[144:147], v[202:205], v[28:31]
	v_mfma_f32_16x16x32_bf16 v[24:27], v[160:163], v[202:205], v[24:27]
	v_mfma_f32_16x16x32_bf16 v[12:15], v[144:147], v[210:213], v[12:15]
	v_mfma_f32_16x16x32_bf16 v[8:11], v[160:163], v[210:213], v[8:11]
	v_mfma_f32_16x16x32_bf16 v[60:63], v[156:159], v[190:193], v[60:63]
	v_mfma_f32_16x16x32_bf16 v[56:59], v[164:167], v[190:193], v[56:59]
	v_mfma_f32_16x16x32_bf16 v[44:47], v[156:159], v[198:201], v[44:47]
	v_mfma_f32_16x16x32_bf16 v[40:43], v[164:167], v[198:201], v[40:43]
	v_mfma_f32_16x16x32_bf16 v[28:31], v[156:159], v[206:209], v[28:31]
	v_mfma_f32_16x16x32_bf16 v[24:27], v[164:167], v[206:209], v[24:27]
	v_mfma_f32_16x16x32_bf16 v[12:15], v[156:159], v[214:217], v[12:15]
	v_mfma_f32_16x16x32_bf16 v[8:11], v[164:167], v[214:217], v[8:11]
	v_mfma_f32_16x16x32_bf16 v[52:55], v[168:171], v[186:189], v[52:55]
	v_mfma_f32_16x16x32_bf16 v[48:51], v[176:179], v[186:189], v[48:51]
	v_mfma_f32_16x16x32_bf16 v[36:39], v[168:171], v[194:197], v[36:39]
	v_mfma_f32_16x16x32_bf16 v[32:35], v[176:179], v[194:197], v[32:35]
	v_mfma_f32_16x16x32_bf16 v[20:23], v[168:171], v[202:205], v[20:23]
	v_mfma_f32_16x16x32_bf16 v[16:19], v[176:179], v[202:205], v[16:19]
	v_mfma_f32_16x16x32_bf16 v[4:7], v[168:171], v[210:213], v[4:7]
	v_mfma_f32_16x16x32_bf16 v[0:3], v[176:179], v[210:213], v[0:3]
	v_mfma_f32_16x16x32_bf16 v[52:55], v[172:175], v[190:193], v[52:55]
	v_mfma_f32_16x16x32_bf16 v[48:51], v[182:185], v[190:193], v[48:51]
	v_mfma_f32_16x16x32_bf16 v[36:39], v[172:175], v[198:201], v[36:39]
	v_mfma_f32_16x16x32_bf16 v[32:35], v[182:185], v[198:201], v[32:35]
	v_mfma_f32_16x16x32_bf16 v[20:23], v[172:175], v[206:209], v[20:23]
	v_mfma_f32_16x16x32_bf16 v[16:19], v[182:185], v[206:209], v[16:19]
	s_setprio 3
	s_barrier
	v_mfma_f32_16x16x32_bf16 v[4:7], v[172:175], v[214:217], v[4:7]
	v_mfma_f32_16x16x32_bf16 v[0:3], v[182:185], v[214:217], v[0:3]
	s_setprio 0
	v_lshl_add_u64 v[218:219], v[222:223], 0, s[12:13]
	s_mov_b32 m0, s35
	s_nop 0
	global_load_lds_dwordx4 v[218:219], off
	v_lshl_add_u64 v[218:219], v[224:225], 0, s[12:13]
	s_mov_b32 m0, s36
	s_nop 0
	global_load_lds_dwordx4 v[218:219], off
	s_add_i32 s45, s45, 2
	s_add_u32 s43, s43, 0x100
	s_addc_u32 s44, s44, 0
	s_cmp_gt_u32 s45, 41
	s_mov_b64 s[18:19], s[20:21]
	s_cbranch_scc0 .LBB0_1461
	s_and_b64 vcc, exec, s[14:15]
	s_cbranch_vccz .LBB0_1464
	s_barrier
